# all s_setprio removed from the GEMM K-loops (priority A/B, step 1 of static-priority strategy)
# baseline (speedup 1.0000x reference)
.LBB0_271:
	s_ashr_i32 s63, s62, 31
	s_lshl_b64 s[0:1], s[62:63], 20
	s_add_u32 s66, s49, s0
	s_addc_u32 s67, s82, s1
	s_and_b64 s[0:1], s[4:5], exec
	s_cselect_b32 s0, s67, s75
	s_cselect_b32 s1, s66, s74
	s_ashr_i32 s65, s64, 31
	s_lshl_b64 s[68:69], s[64:65], 20
	s_add_u32 s68, s45, s68
	s_addc_u32 s69, s47, s69
	s_and_b64 s[78:79], s[4:5], exec
	s_cselect_b32 s3, s69, s77
	s_cselect_b32 s63, s68, s76
	s_add_u32 s74, s74, 0x80080
	s_addc_u32 s75, s75, 0
	s_add_u32 s65, s76, 0x100
	s_addc_u32 s71, s77, 0
	s_mov_b32 s90, -2
	s_waitcnt vmcnt(0)
	ds_read_b128 v[146:149], v166
	ds_read_b128 v[150:153], v166 offset:1024
	ds_read_b128 v[154:157], v166 offset:2048
	ds_read_b128 v[170:173], v166 offset:3072
	ds_read_b128 v[174:177], v167
	ds_read_b128 v[178:181], v167 offset:1024
	ds_read_b128 v[182:185], v167 offset:2048
	ds_read_b128 v[186:189], v167 offset:3072
	s_add_u32 s76, s74, 0xfff80080
	s_addc_u32 s77, s75, -1
	s_cmp_eq_u32 s90, 28
	s_cselect_b32 s79, s0, s77
	s_cselect_b32 s78, s1, s76
	s_cselect_b32 s77, s3, s71
	s_cselect_b32 s76, s63, s65
	s_add_i32 m0, s31, 0xc000
	ds_read_b128 v[190:193], v168
	ds_read_b128 v[194:197], v168 offset:1024
	ds_read_b128 v[198:201], v168 offset:2048
	ds_read_b128 v[202:205], v168 offset:3072
	ds_read_b128 v[206:209], v168 offset:4096
	ds_read_b128 v[214:217], v168 offset:5120
	ds_read_b128 v[218:221], v168 offset:6144
	ds_read_b128 v[222:225], v168 offset:7168
	global_load_lds_dwordx4 v138, s[74:75]
	s_add_i32 m0, s31, 0xe000
	s_nop 0
	global_load_lds_dwordx4 v140, s[74:75]
	s_waitcnt vmcnt(8)
	s_waitcnt lgkmcnt(0)
	s_barrier
	v_mfma_f32_16x16x32_bf16 v[124:127], v[146:149], v[190:193], 0
	v_mfma_f32_16x16x32_bf16 v[120:123], v[154:157], v[190:193], 0
	v_mfma_f32_16x16x32_bf16 v[108:111], v[146:149], v[198:201], 0
	v_mfma_f32_16x16x32_bf16 v[104:107], v[154:157], v[198:201], 0
	v_mfma_f32_16x16x32_bf16 v[92:95], v[146:149], v[206:209], 0
	v_mfma_f32_16x16x32_bf16 v[88:91], v[154:157], v[206:209], 0
	v_mfma_f32_16x16x32_bf16 v[76:79], v[146:149], v[218:221], 0
	v_mfma_f32_16x16x32_bf16 v[72:75], v[154:157], v[218:221], 0
	v_mfma_f32_16x16x32_bf16 v[124:127], v[150:153], v[194:197], v[124:127]
	v_mfma_f32_16x16x32_bf16 v[120:123], v[170:173], v[194:197], v[120:123]
	v_mfma_f32_16x16x32_bf16 v[108:111], v[150:153], v[202:205], v[108:111]
	v_mfma_f32_16x16x32_bf16 v[104:107], v[170:173], v[202:205], v[104:107]
	v_mfma_f32_16x16x32_bf16 v[92:95], v[150:153], v[214:217], v[92:95]
	v_mfma_f32_16x16x32_bf16 v[88:91], v[170:173], v[214:217], v[88:91]
	v_mfma_f32_16x16x32_bf16 v[76:79], v[150:153], v[222:225], v[76:79]
	v_mfma_f32_16x16x32_bf16 v[72:75], v[170:173], v[222:225], v[72:75]
	v_mfma_f32_16x16x32_bf16 v[116:119], v[174:177], v[190:193], 0
	v_mfma_f32_16x16x32_bf16 v[112:115], v[182:185], v[190:193], 0
	v_mfma_f32_16x16x32_bf16 v[100:103], v[174:177], v[198:201], 0
	v_mfma_f32_16x16x32_bf16 v[96:99], v[182:185], v[198:201], 0
	v_mfma_f32_16x16x32_bf16 v[84:87], v[174:177], v[206:209], 0
	v_mfma_f32_16x16x32_bf16 v[80:83], v[182:185], v[206:209], 0
	v_mfma_f32_16x16x32_bf16 v[68:71], v[174:177], v[218:221], 0
	v_mfma_f32_16x16x32_bf16 v[64:67], v[182:185], v[218:221], 0
	v_mfma_f32_16x16x32_bf16 v[116:119], v[178:181], v[194:197], v[116:119]
	v_mfma_f32_16x16x32_bf16 v[112:115], v[186:189], v[194:197], v[112:115]
	v_mfma_f32_16x16x32_bf16 v[100:103], v[178:181], v[202:205], v[100:103]
	v_mfma_f32_16x16x32_bf16 v[96:99], v[186:189], v[202:205], v[96:99]
	v_mfma_f32_16x16x32_bf16 v[84:87], v[178:181], v[214:217], v[84:87]
	v_mfma_f32_16x16x32_bf16 v[80:83], v[186:189], v[214:217], v[80:83]
	v_mfma_f32_16x16x32_bf16 v[68:71], v[178:181], v[222:225], v[68:71]
	v_mfma_f32_16x16x32_bf16 v[64:67], v[186:189], v[222:225], v[64:67]
	s_barrier
	s_add_i32 s91, s81, s30
	s_add_u32 s98, s76, s34
	s_addc_u32 s99, s77, s35
	s_mov_b32 m0, s91
	ds_read_b128 v[190:193], v168 offset:16384
	ds_read_b128 v[194:197], v168 offset:17408
	ds_read_b128 v[198:201], v168 offset:18432
	ds_read_b128 v[202:205], v168 offset:19456
	ds_read_b128 v[206:209], v168 offset:20480
	ds_read_b128 v[214:217], v168 offset:21504
	ds_read_b128 v[218:221], v168 offset:22528
	ds_read_b128 v[222:225], v168 offset:23552
	global_load_lds_dwordx4 v130, s[76:77]
	s_add_i32 m0, s91, 0x2000
	s_add_u32 s92, s76, 0x80000
	s_addc_u32 s93, s77, 0
	s_add_i32 s91, s83, s30
	global_load_lds_dwordx4 v134, s[76:77]
	s_mov_b32 m0, s91
	s_add_u32 s100, s78, s34
	s_addc_u32 s101, s79, s35
	global_load_lds_dwordx4 v130, s[92:93]
	s_add_i32 m0, s91, 0x2000
	s_nop 0
	global_load_lds_dwordx4 v134, s[92:93]
	s_mov_b32 m0, s31
	s_nop 0
	global_load_lds_dwordx4 v128, s[78:79]
	s_mov_b32 m0, s51
	s_nop 0
	global_load_lds_dwordx4 v132, s[78:79]
	s_waitcnt vmcnt(8)
	s_waitcnt lgkmcnt(0)
	s_barrier
	v_mfma_f32_16x16x32_bf16 v[60:63], v[146:149], v[190:193], 0
	v_mfma_f32_16x16x32_bf16 v[56:59], v[154:157], v[190:193], 0
	v_mfma_f32_16x16x32_bf16 v[44:47], v[146:149], v[198:201], 0
	v_mfma_f32_16x16x32_bf16 v[40:43], v[154:157], v[198:201], 0
	v_mfma_f32_16x16x32_bf16 v[28:31], v[146:149], v[206:209], 0
	v_mfma_f32_16x16x32_bf16 v[24:27], v[154:157], v[206:209], 0
	v_mfma_f32_16x16x32_bf16 v[12:15], v[146:149], v[218:221], 0
	v_mfma_f32_16x16x32_bf16 v[8:11], v[154:157], v[218:221], 0
	v_mfma_f32_16x16x32_bf16 v[60:63], v[150:153], v[194:197], v[60:63]
	v_mfma_f32_16x16x32_bf16 v[56:59], v[170:173], v[194:197], v[56:59]
	v_mfma_f32_16x16x32_bf16 v[44:47], v[150:153], v[202:205], v[44:47]
	v_mfma_f32_16x16x32_bf16 v[40:43], v[170:173], v[202:205], v[40:43]
	v_mfma_f32_16x16x32_bf16 v[28:31], v[150:153], v[214:217], v[28:31]
	v_mfma_f32_16x16x32_bf16 v[24:27], v[170:173], v[214:217], v[24:27]
	v_mfma_f32_16x16x32_bf16 v[12:15], v[150:153], v[222:225], v[12:15]
	v_mfma_f32_16x16x32_bf16 v[8:11], v[170:173], v[222:225], v[8:11]
	v_mfma_f32_16x16x32_bf16 v[52:55], v[174:177], v[190:193], 0
	v_mfma_f32_16x16x32_bf16 v[48:51], v[182:185], v[190:193], 0
	v_mfma_f32_16x16x32_bf16 v[36:39], v[174:177], v[198:201], 0
	v_mfma_f32_16x16x32_bf16 v[32:35], v[182:185], v[198:201], 0
	v_mfma_f32_16x16x32_bf16 v[20:23], v[174:177], v[206:209], 0
	v_mfma_f32_16x16x32_bf16 v[16:19], v[182:185], v[206:209], 0
	v_mfma_f32_16x16x32_bf16 v[4:7], v[174:177], v[218:221], 0
	v_mfma_f32_16x16x32_bf16 v[0:3], v[182:185], v[218:221], 0
	v_mfma_f32_16x16x32_bf16 v[52:55], v[178:181], v[194:197], v[52:55]
	v_mfma_f32_16x16x32_bf16 v[48:51], v[186:189], v[194:197], v[48:51]
	v_mfma_f32_16x16x32_bf16 v[36:39], v[178:181], v[202:205], v[36:39]
	v_mfma_f32_16x16x32_bf16 v[32:35], v[186:189], v[202:205], v[32:35]
	v_mfma_f32_16x16x32_bf16 v[20:23], v[178:181], v[214:217], v[20:23]
	v_mfma_f32_16x16x32_bf16 v[16:19], v[186:189], v[214:217], v[16:19]
	v_mfma_f32_16x16x32_bf16 v[4:7], v[178:181], v[222:225], v[4:7]
	v_mfma_f32_16x16x32_bf16 v[0:3], v[186:189], v[222:225], v[0:3]
	s_barrier
	s_add_i32 s91, 0, 0x18000
	v_add_u32_e32 v136, s91, v162
	s_add_i32 s92, 0, 0x1c000
	ds_read_b128 v[146:149], v136
	ds_read_b128 v[150:153], v136 offset:1024
	ds_read_b128 v[154:157], v136 offset:2048
	ds_read_b128 v[170:173], v136 offset:3072
	v_add_u32_e32 v136, s92, v162
	ds_read_b128 v[174:177], v136
	ds_read_b128 v[178:181], v136 offset:1024
	ds_read_b128 v[182:185], v136 offset:2048
	ds_read_b128 v[186:189], v136 offset:3072
	s_add_u32 s78, s78, 0x80000
	s_addc_u32 s79, s79, 0
	s_mov_b32 m0, s28
	ds_read_b128 v[190:193], v168 offset:32768
	ds_read_b128 v[194:197], v168 offset:33792
	ds_read_b128 v[198:201], v168 offset:34816
	ds_read_b128 v[202:205], v168 offset:35840
	ds_read_b128 v[206:209], v168 offset:36864
	ds_read_b128 v[214:217], v168 offset:37888
	ds_read_b128 v[218:221], v168 offset:38912
	ds_read_b128 v[222:225], v168 offset:39936
	global_load_lds_dwordx4 v128, s[78:79]
	s_mov_b32 m0, s29
	s_nop 0
	global_load_lds_dwordx4 v132, s[78:79]
	s_waitcnt vmcnt(8)
	s_waitcnt lgkmcnt(0)
	s_barrier
	v_mfma_f32_16x16x32_bf16 v[124:127], v[146:149], v[190:193], v[124:127]
	v_mfma_f32_16x16x32_bf16 v[120:123], v[154:157], v[190:193], v[120:123]
	v_mfma_f32_16x16x32_bf16 v[108:111], v[146:149], v[198:201], v[108:111]
	v_mfma_f32_16x16x32_bf16 v[104:107], v[154:157], v[198:201], v[104:107]
	v_mfma_f32_16x16x32_bf16 v[92:95], v[146:149], v[206:209], v[92:95]
	v_mfma_f32_16x16x32_bf16 v[88:91], v[154:157], v[206:209], v[88:91]
	v_mfma_f32_16x16x32_bf16 v[76:79], v[146:149], v[218:221], v[76:79]
	v_mfma_f32_16x16x32_bf16 v[72:75], v[154:157], v[218:221], v[72:75]
	v_mfma_f32_16x16x32_bf16 v[124:127], v[150:153], v[194:197], v[124:127]
	v_mfma_f32_16x16x32_bf16 v[120:123], v[170:173], v[194:197], v[120:123]
	v_mfma_f32_16x16x32_bf16 v[108:111], v[150:153], v[202:205], v[108:111]
	v_mfma_f32_16x16x32_bf16 v[104:107], v[170:173], v[202:205], v[104:107]
	v_mfma_f32_16x16x32_bf16 v[92:95], v[150:153], v[214:217], v[92:95]
	v_mfma_f32_16x16x32_bf16 v[88:91], v[170:173], v[214:217], v[88:91]
	v_mfma_f32_16x16x32_bf16 v[76:79], v[150:153], v[222:225], v[76:79]
	v_mfma_f32_16x16x32_bf16 v[72:75], v[170:173], v[222:225], v[72:75]
	v_mfma_f32_16x16x32_bf16 v[116:119], v[174:177], v[190:193], v[116:119]
	v_mfma_f32_16x16x32_bf16 v[112:115], v[182:185], v[190:193], v[112:115]
	v_mfma_f32_16x16x32_bf16 v[100:103], v[174:177], v[198:201], v[100:103]
	v_mfma_f32_16x16x32_bf16 v[96:99], v[182:185], v[198:201], v[96:99]
	v_mfma_f32_16x16x32_bf16 v[84:87], v[174:177], v[206:209], v[84:87]
	v_mfma_f32_16x16x32_bf16 v[80:83], v[182:185], v[206:209], v[80:83]
	v_mfma_f32_16x16x32_bf16 v[68:71], v[174:177], v[218:221], v[68:71]
	v_mfma_f32_16x16x32_bf16 v[64:67], v[182:185], v[218:221], v[64:67]
	v_mfma_f32_16x16x32_bf16 v[116:119], v[178:181], v[194:197], v[116:119]
	v_mfma_f32_16x16x32_bf16 v[112:115], v[186:189], v[194:197], v[112:115]
	v_mfma_f32_16x16x32_bf16 v[100:103], v[178:181], v[202:205], v[100:103]
	v_mfma_f32_16x16x32_bf16 v[96:99], v[186:189], v[202:205], v[96:99]
	v_mfma_f32_16x16x32_bf16 v[84:87], v[178:181], v[214:217], v[84:87]
	v_mfma_f32_16x16x32_bf16 v[80:83], v[186:189], v[214:217], v[80:83]
	v_mfma_f32_16x16x32_bf16 v[68:71], v[178:181], v[222:225], v[68:71]
	v_mfma_f32_16x16x32_bf16 v[64:67], v[186:189], v[222:225], v[64:67]
	s_barrier
	s_add_i32 s78, s91, s30
	s_mov_b32 m0, s78
	ds_read_b128 v[190:193], v168 offset:49152
	ds_read_b128 v[194:197], v168 offset:50176
	ds_read_b128 v[198:201], v168 offset:51200
	ds_read_b128 v[202:205], v168 offset:52224
	ds_read_b128 v[206:209], v168 offset:53248
	ds_read_b128 v[214:217], v168 offset:54272
	ds_read_b128 v[218:221], v168 offset:55296
	ds_read_b128 v[222:225], v168 offset:56320
	global_load_lds_dwordx4 v130, s[98:99]
	s_add_i32 m0, s78, 0x2000
	s_add_u32 s76, s76, 0x80080
	s_addc_u32 s77, s77, 0
	s_add_i32 s78, s92, s30
	global_load_lds_dwordx4 v134, s[98:99]
	s_mov_b32 m0, s78
	s_nop 0
	global_load_lds_dwordx4 v130, s[76:77]
	s_add_i32 m0, s78, 0x2000
	s_nop 0
	global_load_lds_dwordx4 v134, s[76:77]
	s_mov_b32 m0, s73
	s_nop 0
	global_load_lds_dwordx4 v128, s[100:101]
	s_mov_b32 m0, s80
	s_nop 0
	global_load_lds_dwordx4 v132, s[100:101]
	s_waitcnt vmcnt(8)
	s_waitcnt lgkmcnt(0)
	s_barrier
	v_mfma_f32_16x16x32_bf16 v[60:63], v[146:149], v[190:193], v[60:63]
	v_mfma_f32_16x16x32_bf16 v[56:59], v[154:157], v[190:193], v[56:59]
	v_mfma_f32_16x16x32_bf16 v[44:47], v[146:149], v[198:201], v[44:47]
	v_mfma_f32_16x16x32_bf16 v[40:43], v[154:157], v[198:201], v[40:43]
	v_mfma_f32_16x16x32_bf16 v[28:31], v[146:149], v[206:209], v[28:31]
	v_mfma_f32_16x16x32_bf16 v[24:27], v[154:157], v[206:209], v[24:27]
	v_mfma_f32_16x16x32_bf16 v[12:15], v[146:149], v[218:221], v[12:15]
	v_mfma_f32_16x16x32_bf16 v[8:11], v[154:157], v[218:221], v[8:11]
	v_mfma_f32_16x16x32_bf16 v[60:63], v[150:153], v[194:197], v[60:63]
	v_mfma_f32_16x16x32_bf16 v[56:59], v[170:173], v[194:197], v[56:59]
	v_mfma_f32_16x16x32_bf16 v[44:47], v[150:153], v[202:205], v[44:47]
	v_mfma_f32_16x16x32_bf16 v[40:43], v[170:173], v[202:205], v[40:43]
	v_mfma_f32_16x16x32_bf16 v[28:31], v[150:153], v[214:217], v[28:31]
	v_mfma_f32_16x16x32_bf16 v[24:27], v[170:173], v[214:217], v[24:27]
	v_mfma_f32_16x16x32_bf16 v[12:15], v[150:153], v[222:225], v[12:15]
	v_mfma_f32_16x16x32_bf16 v[8:11], v[170:173], v[222:225], v[8:11]
	v_mfma_f32_16x16x32_bf16 v[52:55], v[174:177], v[190:193], v[52:55]
	v_mfma_f32_16x16x32_bf16 v[48:51], v[182:185], v[190:193], v[48:51]
	v_mfma_f32_16x16x32_bf16 v[36:39], v[174:177], v[198:201], v[36:39]
	v_mfma_f32_16x16x32_bf16 v[32:35], v[182:185], v[198:201], v[32:35]
	v_mfma_f32_16x16x32_bf16 v[20:23], v[174:177], v[206:209], v[20:23]
	v_mfma_f32_16x16x32_bf16 v[16:19], v[182:185], v[206:209], v[16:19]
	v_mfma_f32_16x16x32_bf16 v[4:7], v[174:177], v[218:221], v[4:7]
	v_mfma_f32_16x16x32_bf16 v[0:3], v[182:185], v[218:221], v[0:3]
	v_mfma_f32_16x16x32_bf16 v[52:55], v[178:181], v[194:197], v[52:55]
	v_mfma_f32_16x16x32_bf16 v[48:51], v[186:189], v[194:197], v[48:51]
	v_mfma_f32_16x16x32_bf16 v[36:39], v[178:181], v[202:205], v[36:39]
	v_mfma_f32_16x16x32_bf16 v[32:35], v[186:189], v[202:205], v[32:35]
	v_mfma_f32_16x16x32_bf16 v[20:23], v[178:181], v[214:217], v[20:23]
	v_mfma_f32_16x16x32_bf16 v[16:19], v[186:189], v[214:217], v[16:19]
	v_mfma_f32_16x16x32_bf16 v[4:7], v[178:181], v[222:225], v[4:7]
	v_mfma_f32_16x16x32_bf16 v[0:3], v[186:189], v[222:225], v[0:3]
	s_barrier
	s_add_i32 s90, s90, 2
	s_add_u32 s74, s74, 0x100
	s_addc_u32 s75, s75, 0
	s_add_u32 s65, s65, 0x100
	s_addc_u32 s71, s71, 0
	s_cmp_gt_u32 s90, 29
.LBB0_272:
	ds_read_b128 v[146:149], v166
	ds_read_b128 v[150:153], v166 offset:1024
	ds_read_b128 v[154:157], v166 offset:2048
	ds_read_b128 v[170:173], v166 offset:3072
	ds_read_b128 v[174:177], v167
	ds_read_b128 v[178:181], v167 offset:1024
	ds_read_b128 v[182:185], v167 offset:2048
	ds_read_b128 v[186:189], v167 offset:3072
	s_add_u32 s76, s74, 0xfff80080
	s_addc_u32 s77, s75, -1
	s_cmp_eq_u32 s90, 28
	s_cselect_b32 s79, s0, s77
	s_cselect_b32 s78, s1, s76
	s_cselect_b32 s77, s3, s71
	s_cselect_b32 s76, s63, s65
	s_add_i32 m0, s31, 0xc000
	ds_read_b128 v[190:193], v168
	ds_read_b128 v[194:197], v168 offset:1024
	ds_read_b128 v[198:201], v168 offset:2048
	ds_read_b128 v[202:205], v168 offset:3072
	ds_read_b128 v[206:209], v168 offset:4096
	ds_read_b128 v[214:217], v168 offset:5120
	ds_read_b128 v[218:221], v168 offset:6144
	ds_read_b128 v[222:225], v168 offset:7168
	global_load_lds_dwordx4 v138, s[74:75]
	s_add_i32 m0, s31, 0xe000
	s_nop 0
	global_load_lds_dwordx4 v140, s[74:75]
	s_waitcnt vmcnt(8)
	s_waitcnt lgkmcnt(0)
	s_barrier
	v_mfma_f32_16x16x32_bf16 v[124:127], v[146:149], v[190:193], v[124:127]
	v_mfma_f32_16x16x32_bf16 v[120:123], v[154:157], v[190:193], v[120:123]
	v_mfma_f32_16x16x32_bf16 v[108:111], v[146:149], v[198:201], v[108:111]
	v_mfma_f32_16x16x32_bf16 v[104:107], v[154:157], v[198:201], v[104:107]
	v_mfma_f32_16x16x32_bf16 v[92:95], v[146:149], v[206:209], v[92:95]
	v_mfma_f32_16x16x32_bf16 v[88:91], v[154:157], v[206:209], v[88:91]
	v_mfma_f32_16x16x32_bf16 v[76:79], v[146:149], v[218:221], v[76:79]
	v_mfma_f32_16x16x32_bf16 v[72:75], v[154:157], v[218:221], v[72:75]
	v_mfma_f32_16x16x32_bf16 v[124:127], v[150:153], v[194:197], v[124:127]
	v_mfma_f32_16x16x32_bf16 v[120:123], v[170:173], v[194:197], v[120:123]
	v_mfma_f32_16x16x32_bf16 v[108:111], v[150:153], v[202:205], v[108:111]
	v_mfma_f32_16x16x32_bf16 v[104:107], v[170:173], v[202:205], v[104:107]
	v_mfma_f32_16x16x32_bf16 v[92:95], v[150:153], v[214:217], v[92:95]
	v_mfma_f32_16x16x32_bf16 v[88:91], v[170:173], v[214:217], v[88:91]
	v_mfma_f32_16x16x32_bf16 v[76:79], v[150:153], v[222:225], v[76:79]
	v_mfma_f32_16x16x32_bf16 v[72:75], v[170:173], v[222:225], v[72:75]
	v_mfma_f32_16x16x32_bf16 v[116:119], v[174:177], v[190:193], v[116:119]
	v_mfma_f32_16x16x32_bf16 v[112:115], v[182:185], v[190:193], v[112:115]
	v_mfma_f32_16x16x32_bf16 v[100:103], v[174:177], v[198:201], v[100:103]
	v_mfma_f32_16x16x32_bf16 v[96:99], v[182:185], v[198:201], v[96:99]
	v_mfma_f32_16x16x32_bf16 v[84:87], v[174:177], v[206:209], v[84:87]
	v_mfma_f32_16x16x32_bf16 v[80:83], v[182:185], v[206:209], v[80:83]
	v_mfma_f32_16x16x32_bf16 v[68:71], v[174:177], v[218:221], v[68:71]
	v_mfma_f32_16x16x32_bf16 v[64:67], v[182:185], v[218:221], v[64:67]
	v_mfma_f32_16x16x32_bf16 v[116:119], v[178:181], v[194:197], v[116:119]
	v_mfma_f32_16x16x32_bf16 v[112:115], v[186:189], v[194:197], v[112:115]
	v_mfma_f32_16x16x32_bf16 v[100:103], v[178:181], v[202:205], v[100:103]
	v_mfma_f32_16x16x32_bf16 v[96:99], v[186:189], v[202:205], v[96:99]
	v_mfma_f32_16x16x32_bf16 v[84:87], v[178:181], v[214:217], v[84:87]
	v_mfma_f32_16x16x32_bf16 v[80:83], v[186:189], v[214:217], v[80:83]
	v_mfma_f32_16x16x32_bf16 v[68:71], v[178:181], v[222:225], v[68:71]
	v_mfma_f32_16x16x32_bf16 v[64:67], v[186:189], v[222:225], v[64:67]
	s_barrier
	s_add_i32 s91, s81, s30
	s_add_u32 s98, s76, s34
	s_addc_u32 s99, s77, s35
	s_mov_b32 m0, s91
	ds_read_b128 v[190:193], v168 offset:16384
	ds_read_b128 v[194:197], v168 offset:17408
	ds_read_b128 v[198:201], v168 offset:18432
	ds_read_b128 v[202:205], v168 offset:19456
	ds_read_b128 v[206:209], v168 offset:20480
	ds_read_b128 v[214:217], v168 offset:21504
	ds_read_b128 v[218:221], v168 offset:22528
	ds_read_b128 v[222:225], v168 offset:23552
	global_load_lds_dwordx4 v130, s[76:77]
	s_add_i32 m0, s91, 0x2000
	s_add_u32 s92, s76, 0x80000
	s_addc_u32 s93, s77, 0
	s_add_i32 s91, s83, s30
	global_load_lds_dwordx4 v134, s[76:77]
	s_mov_b32 m0, s91
	s_add_u32 s100, s78, s34
	s_addc_u32 s101, s79, s35
	global_load_lds_dwordx4 v130, s[92:93]
	s_add_i32 m0, s91, 0x2000
	s_nop 0
	global_load_lds_dwordx4 v134, s[92:93]
	s_mov_b32 m0, s31
	s_nop 0
	global_load_lds_dwordx4 v128, s[78:79]
	s_mov_b32 m0, s51
	s_nop 0
	global_load_lds_dwordx4 v132, s[78:79]
	s_waitcnt vmcnt(8)
	s_waitcnt lgkmcnt(0)
	s_barrier
	v_mfma_f32_16x16x32_bf16 v[60:63], v[146:149], v[190:193], v[60:63]
	v_mfma_f32_16x16x32_bf16 v[56:59], v[154:157], v[190:193], v[56:59]
	v_mfma_f32_16x16x32_bf16 v[44:47], v[146:149], v[198:201], v[44:47]
	v_mfma_f32_16x16x32_bf16 v[40:43], v[154:157], v[198:201], v[40:43]
	v_mfma_f32_16x16x32_bf16 v[28:31], v[146:149], v[206:209], v[28:31]
	v_mfma_f32_16x16x32_bf16 v[24:27], v[154:157], v[206:209], v[24:27]
	v_mfma_f32_16x16x32_bf16 v[12:15], v[146:149], v[218:221], v[12:15]
	v_mfma_f32_16x16x32_bf16 v[8:11], v[154:157], v[218:221], v[8:11]
	v_mfma_f32_16x16x32_bf16 v[60:63], v[150:153], v[194:197], v[60:63]
	v_mfma_f32_16x16x32_bf16 v[56:59], v[170:173], v[194:197], v[56:59]
	v_mfma_f32_16x16x32_bf16 v[44:47], v[150:153], v[202:205], v[44:47]
	v_mfma_f32_16x16x32_bf16 v[40:43], v[170:173], v[202:205], v[40:43]
	v_mfma_f32_16x16x32_bf16 v[28:31], v[150:153], v[214:217], v[28:31]
	v_mfma_f32_16x16x32_bf16 v[24:27], v[170:173], v[214:217], v[24:27]
	v_mfma_f32_16x16x32_bf16 v[12:15], v[150:153], v[222:225], v[12:15]
	v_mfma_f32_16x16x32_bf16 v[8:11], v[170:173], v[222:225], v[8:11]
	v_mfma_f32_16x16x32_bf16 v[52:55], v[174:177], v[190:193], v[52:55]
	v_mfma_f32_16x16x32_bf16 v[48:51], v[182:185], v[190:193], v[48:51]
	v_mfma_f32_16x16x32_bf16 v[36:39], v[174:177], v[198:201], v[36:39]
	v_mfma_f32_16x16x32_bf16 v[32:35], v[182:185], v[198:201], v[32:35]
	v_mfma_f32_16x16x32_bf16 v[20:23], v[174:177], v[206:209], v[20:23]
	v_mfma_f32_16x16x32_bf16 v[16:19], v[182:185], v[206:209], v[16:19]
	v_mfma_f32_16x16x32_bf16 v[4:7], v[174:177], v[218:221], v[4:7]
	v_mfma_f32_16x16x32_bf16 v[0:3], v[182:185], v[218:221], v[0:3]
	v_mfma_f32_16x16x32_bf16 v[52:55], v[178:181], v[194:197], v[52:55]
	v_mfma_f32_16x16x32_bf16 v[48:51], v[186:189], v[194:197], v[48:51]
	v_mfma_f32_16x16x32_bf16 v[36:39], v[178:181], v[202:205], v[36:39]
	v_mfma_f32_16x16x32_bf16 v[32:35], v[186:189], v[202:205], v[32:35]
	v_mfma_f32_16x16x32_bf16 v[20:23], v[178:181], v[214:217], v[20:23]
	v_mfma_f32_16x16x32_bf16 v[16:19], v[186:189], v[214:217], v[16:19]
	v_mfma_f32_16x16x32_bf16 v[4:7], v[178:181], v[222:225], v[4:7]
	v_mfma_f32_16x16x32_bf16 v[0:3], v[186:189], v[222:225], v[0:3]
	s_barrier
	s_add_i32 s91, 0, 0x18000
	v_add_u32_e32 v136, s91, v162
	s_add_i32 s92, 0, 0x1c000
	ds_read_b128 v[146:149], v136
	ds_read_b128 v[150:153], v136 offset:1024
	ds_read_b128 v[154:157], v136 offset:2048
	ds_read_b128 v[170:173], v136 offset:3072
	v_add_u32_e32 v136, s92, v162
	ds_read_b128 v[174:177], v136
	ds_read_b128 v[178:181], v136 offset:1024
	ds_read_b128 v[182:185], v136 offset:2048
	ds_read_b128 v[186:189], v136 offset:3072
	s_add_u32 s78, s78, 0x80000
	s_addc_u32 s79, s79, 0
	s_mov_b32 m0, s28
	ds_read_b128 v[190:193], v168 offset:32768
	ds_read_b128 v[194:197], v168 offset:33792
	ds_read_b128 v[198:201], v168 offset:34816
	ds_read_b128 v[202:205], v168 offset:35840
	ds_read_b128 v[206:209], v168 offset:36864
	ds_read_b128 v[214:217], v168 offset:37888
	ds_read_b128 v[218:221], v168 offset:38912
	ds_read_b128 v[222:225], v168 offset:39936
	global_load_lds_dwordx4 v128, s[78:79]
	s_mov_b32 m0, s29
	s_nop 0
	global_load_lds_dwordx4 v132, s[78:79]
	s_waitcnt vmcnt(8)
	s_waitcnt lgkmcnt(0)
	s_barrier
	v_mfma_f32_16x16x32_bf16 v[124:127], v[146:149], v[190:193], v[124:127]
	v_mfma_f32_16x16x32_bf16 v[120:123], v[154:157], v[190:193], v[120:123]
	v_mfma_f32_16x16x32_bf16 v[108:111], v[146:149], v[198:201], v[108:111]
	v_mfma_f32_16x16x32_bf16 v[104:107], v[154:157], v[198:201], v[104:107]
	v_mfma_f32_16x16x32_bf16 v[92:95], v[146:149], v[206:209], v[92:95]
	v_mfma_f32_16x16x32_bf16 v[88:91], v[154:157], v[206:209], v[88:91]
	v_mfma_f32_16x16x32_bf16 v[76:79], v[146:149], v[218:221], v[76:79]
	v_mfma_f32_16x16x32_bf16 v[72:75], v[154:157], v[218:221], v[72:75]
	v_mfma_f32_16x16x32_bf16 v[124:127], v[150:153], v[194:197], v[124:127]
	v_mfma_f32_16x16x32_bf16 v[120:123], v[170:173], v[194:197], v[120:123]
	v_mfma_f32_16x16x32_bf16 v[108:111], v[150:153], v[202:205], v[108:111]
	v_mfma_f32_16x16x32_bf16 v[104:107], v[170:173], v[202:205], v[104:107]
	v_mfma_f32_16x16x32_bf16 v[92:95], v[150:153], v[214:217], v[92:95]
	v_mfma_f32_16x16x32_bf16 v[88:91], v[170:173], v[214:217], v[88:91]
	v_mfma_f32_16x16x32_bf16 v[76:79], v[150:153], v[222:225], v[76:79]
	v_mfma_f32_16x16x32_bf16 v[72:75], v[170:173], v[222:225], v[72:75]
	v_mfma_f32_16x16x32_bf16 v[116:119], v[174:177], v[190:193], v[116:119]
	v_mfma_f32_16x16x32_bf16 v[112:115], v[182:185], v[190:193], v[112:115]
	v_mfma_f32_16x16x32_bf16 v[100:103], v[174:177], v[198:201], v[100:103]
	v_mfma_f32_16x16x32_bf16 v[96:99], v[182:185], v[198:201], v[96:99]
	v_mfma_f32_16x16x32_bf16 v[84:87], v[174:177], v[206:209], v[84:87]
	v_mfma_f32_16x16x32_bf16 v[80:83], v[182:185], v[206:209], v[80:83]
	v_mfma_f32_16x16x32_bf16 v[68:71], v[174:177], v[218:221], v[68:71]
	v_mfma_f32_16x16x32_bf16 v[64:67], v[182:185], v[218:221], v[64:67]
	v_mfma_f32_16x16x32_bf16 v[116:119], v[178:181], v[194:197], v[116:119]
	v_mfma_f32_16x16x32_bf16 v[112:115], v[186:189], v[194:197], v[112:115]
	v_mfma_f32_16x16x32_bf16 v[100:103], v[178:181], v[202:205], v[100:103]
	v_mfma_f32_16x16x32_bf16 v[96:99], v[186:189], v[202:205], v[96:99]
	v_mfma_f32_16x16x32_bf16 v[84:87], v[178:181], v[214:217], v[84:87]
	v_mfma_f32_16x16x32_bf16 v[80:83], v[186:189], v[214:217], v[80:83]
	v_mfma_f32_16x16x32_bf16 v[68:71], v[178:181], v[222:225], v[68:71]
	v_mfma_f32_16x16x32_bf16 v[64:67], v[186:189], v[222:225], v[64:67]
	s_barrier
	s_add_i32 s78, s91, s30
	s_mov_b32 m0, s78
	ds_read_b128 v[190:193], v168 offset:49152
	ds_read_b128 v[194:197], v168 offset:50176
	ds_read_b128 v[198:201], v168 offset:51200
	ds_read_b128 v[202:205], v168 offset:52224
	ds_read_b128 v[206:209], v168 offset:53248
	ds_read_b128 v[214:217], v168 offset:54272
	ds_read_b128 v[218:221], v168 offset:55296
	ds_read_b128 v[222:225], v168 offset:56320
	global_load_lds_dwordx4 v130, s[98:99]
	s_add_i32 m0, s78, 0x2000
	s_add_u32 s76, s76, 0x80080
	s_addc_u32 s77, s77, 0
	s_add_i32 s78, s92, s30
	global_load_lds_dwordx4 v134, s[98:99]
	s_mov_b32 m0, s78
	s_nop 0
	global_load_lds_dwordx4 v130, s[76:77]
	s_add_i32 m0, s78, 0x2000
	s_nop 0
	global_load_lds_dwordx4 v134, s[76:77]
	s_mov_b32 m0, s73
	s_nop 0
	global_load_lds_dwordx4 v128, s[100:101]
	s_mov_b32 m0, s80
	s_nop 0
	global_load_lds_dwordx4 v132, s[100:101]
	s_waitcnt vmcnt(8)
	s_waitcnt lgkmcnt(0)
	s_barrier
	v_mfma_f32_16x16x32_bf16 v[60:63], v[146:149], v[190:193], v[60:63]
	v_mfma_f32_16x16x32_bf16 v[56:59], v[154:157], v[190:193], v[56:59]
	v_mfma_f32_16x16x32_bf16 v[44:47], v[146:149], v[198:201], v[44:47]
	v_mfma_f32_16x16x32_bf16 v[40:43], v[154:157], v[198:201], v[40:43]
	v_mfma_f32_16x16x32_bf16 v[28:31], v[146:149], v[206:209], v[28:31]
	v_mfma_f32_16x16x32_bf16 v[24:27], v[154:157], v[206:209], v[24:27]
	v_mfma_f32_16x16x32_bf16 v[12:15], v[146:149], v[218:221], v[12:15]
	v_mfma_f32_16x16x32_bf16 v[8:11], v[154:157], v[218:221], v[8:11]
	v_mfma_f32_16x16x32_bf16 v[60:63], v[150:153], v[194:197], v[60:63]
	v_mfma_f32_16x16x32_bf16 v[56:59], v[170:173], v[194:197], v[56:59]
	v_mfma_f32_16x16x32_bf16 v[44:47], v[150:153], v[202:205], v[44:47]
	v_mfma_f32_16x16x32_bf16 v[40:43], v[170:173], v[202:205], v[40:43]
	v_mfma_f32_16x16x32_bf16 v[28:31], v[150:153], v[214:217], v[28:31]
	v_mfma_f32_16x16x32_bf16 v[24:27], v[170:173], v[214:217], v[24:27]
	v_mfma_f32_16x16x32_bf16 v[12:15], v[150:153], v[222:225], v[12:15]
	v_mfma_f32_16x16x32_bf16 v[8:11], v[170:173], v[222:225], v[8:11]
	v_mfma_f32_16x16x32_bf16 v[52:55], v[174:177], v[190:193], v[52:55]
	v_mfma_f32_16x16x32_bf16 v[48:51], v[182:185], v[190:193], v[48:51]
	v_mfma_f32_16x16x32_bf16 v[36:39], v[174:177], v[198:201], v[36:39]
	v_mfma_f32_16x16x32_bf16 v[32:35], v[182:185], v[198:201], v[32:35]
	v_mfma_f32_16x16x32_bf16 v[20:23], v[174:177], v[206:209], v[20:23]
	v_mfma_f32_16x16x32_bf16 v[16:19], v[182:185], v[206:209], v[16:19]
	v_mfma_f32_16x16x32_bf16 v[4:7], v[174:177], v[218:221], v[4:7]
	v_mfma_f32_16x16x32_bf16 v[0:3], v[182:185], v[218:221], v[0:3]
	v_mfma_f32_16x16x32_bf16 v[52:55], v[178:181], v[194:197], v[52:55]
	v_mfma_f32_16x16x32_bf16 v[48:51], v[186:189], v[194:197], v[48:51]
	v_mfma_f32_16x16x32_bf16 v[36:39], v[178:181], v[202:205], v[36:39]
	v_mfma_f32_16x16x32_bf16 v[32:35], v[186:189], v[202:205], v[32:35]
	v_mfma_f32_16x16x32_bf16 v[20:23], v[178:181], v[214:217], v[20:23]
	v_mfma_f32_16x16x32_bf16 v[16:19], v[186:189], v[214:217], v[16:19]
	v_mfma_f32_16x16x32_bf16 v[4:7], v[178:181], v[222:225], v[4:7]
	v_mfma_f32_16x16x32_bf16 v[0:3], v[186:189], v[222:225], v[0:3]
	s_barrier
	s_add_i32 s90, s90, 2
	s_add_u32 s74, s74, 0x100
	s_addc_u32 s75, s75, 0
	s_add_u32 s65, s65, 0x100
	s_addc_u32 s71, s71, 0
	s_cmp_gt_u32 s90, 29
	s_cbranch_scc0 .LBB0_272
	s_and_b64 vcc, exec, s[36:37]
	s_cbranch_vccz .LBB0_275
	s_barrier

.LBB0_542:
	s_ashr_i32 s35, s34, 31
	s_lshl_b64 s[0:1], s[34:35], 20
	s_add_u32 s36, s29, s0
	s_addc_u32 s37, s30, s1
	s_and_b64 s[0:1], s[6:7], exec
	s_cselect_b32 s0, s37, s43
	s_cselect_b32 s1, s36, s42
	s_ashr_i32 s25, s24, 31
	s_lshl_b64 s[38:39], s[24:25], 20
	s_add_u32 s38, s27, s38
	s_addc_u32 s39, s28, s39
	s_and_b64 s[46:47], s[6:7], exec
	s_cselect_b32 s3, s39, s45
	s_cselect_b32 s9, s38, s44
	s_add_u32 s42, s42, 0x80080
	s_addc_u32 s43, s43, 0
	s_add_u32 s25, s44, 0x100
	s_addc_u32 s35, s45, 0
	s_mov_b32 s58, -2
	s_waitcnt lgkmcnt(0)
	s_waitcnt vmcnt(0)
	ds_read_b128 v[128:131], v216
	ds_read_b128 v[132:135], v216 offset:1024
	ds_read_b128 v[136:139], v216 offset:2048
	ds_read_b128 v[140:143], v216 offset:3072
	ds_read_b128 v[144:147], v217
	ds_read_b128 v[148:151], v217 offset:1024
	ds_read_b128 v[152:155], v217 offset:2048
	ds_read_b128 v[156:159], v217 offset:3072
	s_add_u32 s44, s42, 0xfff80080
	s_addc_u32 s45, s43, -1
	s_cmp_eq_u32 s58, 28
	s_cselect_b32 s47, s0, s45
	s_cselect_b32 s46, s1, s44
	s_cselect_b32 s45, s3, s35
	s_cselect_b32 s44, s9, s25
	s_add_i32 m0, s41, 0xc000
	ds_read_b128 v[160:163], v218
	ds_read_b128 v[164:167], v218 offset:1024
	ds_read_b128 v[168:171], v218 offset:2048
	ds_read_b128 v[172:175], v218 offset:3072
	ds_read_b128 v[192:195], v218 offset:4096
	ds_read_b128 v[196:199], v218 offset:5120
	ds_read_b128 v[200:203], v218 offset:6144
	ds_read_b128 v[204:207], v218 offset:7168
	global_load_lds_dwordx4 v184, s[42:43]
	s_add_i32 m0, s41, 0xe000
	s_nop 0
	global_load_lds_dwordx4 v186, s[42:43]
	s_waitcnt vmcnt(8)
	s_waitcnt lgkmcnt(0)
	s_barrier
	v_mfma_f32_16x16x32_bf16 v[124:127], v[128:131], v[160:163], 0
	v_mfma_f32_16x16x32_bf16 v[120:123], v[136:139], v[160:163], 0
	v_mfma_f32_16x16x32_bf16 v[108:111], v[128:131], v[168:171], 0
	v_mfma_f32_16x16x32_bf16 v[104:107], v[136:139], v[168:171], 0
	v_mfma_f32_16x16x32_bf16 v[92:95], v[128:131], v[192:195], 0
	v_mfma_f32_16x16x32_bf16 v[88:91], v[136:139], v[192:195], 0
	v_mfma_f32_16x16x32_bf16 v[76:79], v[128:131], v[200:203], 0
	v_mfma_f32_16x16x32_bf16 v[72:75], v[136:139], v[200:203], 0
	v_mfma_f32_16x16x32_bf16 v[124:127], v[132:135], v[164:167], v[124:127]
	v_mfma_f32_16x16x32_bf16 v[120:123], v[140:143], v[164:167], v[120:123]
	v_mfma_f32_16x16x32_bf16 v[108:111], v[132:135], v[172:175], v[108:111]
	v_mfma_f32_16x16x32_bf16 v[104:107], v[140:143], v[172:175], v[104:107]
	v_mfma_f32_16x16x32_bf16 v[92:95], v[132:135], v[196:199], v[92:95]
	v_mfma_f32_16x16x32_bf16 v[88:91], v[140:143], v[196:199], v[88:91]
	v_mfma_f32_16x16x32_bf16 v[76:79], v[132:135], v[204:207], v[76:79]
	v_mfma_f32_16x16x32_bf16 v[72:75], v[140:143], v[204:207], v[72:75]
	v_mfma_f32_16x16x32_bf16 v[116:119], v[144:147], v[160:163], 0
	v_mfma_f32_16x16x32_bf16 v[112:115], v[152:155], v[160:163], 0
	v_mfma_f32_16x16x32_bf16 v[100:103], v[144:147], v[168:171], 0
	v_mfma_f32_16x16x32_bf16 v[96:99], v[152:155], v[168:171], 0
	v_mfma_f32_16x16x32_bf16 v[84:87], v[144:147], v[192:195], 0
	v_mfma_f32_16x16x32_bf16 v[80:83], v[152:155], v[192:195], 0
	v_mfma_f32_16x16x32_bf16 v[68:71], v[144:147], v[200:203], 0
	v_mfma_f32_16x16x32_bf16 v[64:67], v[152:155], v[200:203], 0
	v_mfma_f32_16x16x32_bf16 v[116:119], v[148:151], v[164:167], v[116:119]
	v_mfma_f32_16x16x32_bf16 v[112:115], v[156:159], v[164:167], v[112:115]
	v_mfma_f32_16x16x32_bf16 v[100:103], v[148:151], v[172:175], v[100:103]
	v_mfma_f32_16x16x32_bf16 v[96:99], v[156:159], v[172:175], v[96:99]
	v_mfma_f32_16x16x32_bf16 v[84:87], v[148:151], v[196:199], v[84:87]
	v_mfma_f32_16x16x32_bf16 v[80:83], v[156:159], v[196:199], v[80:83]
	v_mfma_f32_16x16x32_bf16 v[68:71], v[148:151], v[204:207], v[68:71]
	v_mfma_f32_16x16x32_bf16 v[64:67], v[156:159], v[204:207], v[64:67]
	s_barrier
	s_add_i32 s59, s55, s31
	s_add_u32 s98, s44, s20
	s_addc_u32 s99, s45, s21
	s_mov_b32 m0, s59
	ds_read_b128 v[160:163], v218 offset:16384
	ds_read_b128 v[164:167], v218 offset:17408
	ds_read_b128 v[168:171], v218 offset:18432
	ds_read_b128 v[172:175], v218 offset:19456
	ds_read_b128 v[192:195], v218 offset:20480
	ds_read_b128 v[196:199], v218 offset:21504
	ds_read_b128 v[200:203], v218 offset:22528
	ds_read_b128 v[204:207], v218 offset:23552
	global_load_lds_dwordx4 v178, s[44:45]
	s_add_i32 m0, s59, 0x2000
	s_add_u32 s60, s44, 0x80000
	s_addc_u32 s61, s45, 0
	s_add_i32 s59, s56, s31
	global_load_lds_dwordx4 v182, s[44:45]
	s_mov_b32 m0, s59
	s_add_u32 s100, s46, s20
	s_addc_u32 s101, s47, s21
	global_load_lds_dwordx4 v178, s[60:61]
	s_add_i32 m0, s59, 0x2000
	s_nop 0
	global_load_lds_dwordx4 v182, s[60:61]
	s_mov_b32 m0, s41
	s_nop 0
	global_load_lds_dwordx4 v176, s[46:47]
	s_mov_b32 m0, s48
	s_nop 0
	global_load_lds_dwordx4 v180, s[46:47]
	s_waitcnt vmcnt(8)
	s_waitcnt lgkmcnt(0)
	s_barrier
	v_mfma_f32_16x16x32_bf16 v[60:63], v[128:131], v[160:163], 0
	v_mfma_f32_16x16x32_bf16 v[56:59], v[136:139], v[160:163], 0
	v_mfma_f32_16x16x32_bf16 v[44:47], v[128:131], v[168:171], 0
	v_mfma_f32_16x16x32_bf16 v[40:43], v[136:139], v[168:171], 0
	v_mfma_f32_16x16x32_bf16 v[28:31], v[128:131], v[192:195], 0
	v_mfma_f32_16x16x32_bf16 v[24:27], v[136:139], v[192:195], 0
	v_mfma_f32_16x16x32_bf16 v[12:15], v[128:131], v[200:203], 0
	v_mfma_f32_16x16x32_bf16 v[8:11], v[136:139], v[200:203], 0
	v_mfma_f32_16x16x32_bf16 v[60:63], v[132:135], v[164:167], v[60:63]
	v_mfma_f32_16x16x32_bf16 v[56:59], v[140:143], v[164:167], v[56:59]
	v_mfma_f32_16x16x32_bf16 v[44:47], v[132:135], v[172:175], v[44:47]
	v_mfma_f32_16x16x32_bf16 v[40:43], v[140:143], v[172:175], v[40:43]
	v_mfma_f32_16x16x32_bf16 v[28:31], v[132:135], v[196:199], v[28:31]
	v_mfma_f32_16x16x32_bf16 v[24:27], v[140:143], v[196:199], v[24:27]
	v_mfma_f32_16x16x32_bf16 v[12:15], v[132:135], v[204:207], v[12:15]
	v_mfma_f32_16x16x32_bf16 v[8:11], v[140:143], v[204:207], v[8:11]
	v_mfma_f32_16x16x32_bf16 v[52:55], v[144:147], v[160:163], 0
	v_mfma_f32_16x16x32_bf16 v[48:51], v[152:155], v[160:163], 0
	v_mfma_f32_16x16x32_bf16 v[36:39], v[144:147], v[168:171], 0
	v_mfma_f32_16x16x32_bf16 v[32:35], v[152:155], v[168:171], 0
	v_mfma_f32_16x16x32_bf16 v[20:23], v[144:147], v[192:195], 0
	v_mfma_f32_16x16x32_bf16 v[16:19], v[152:155], v[192:195], 0
	v_mfma_f32_16x16x32_bf16 v[4:7], v[144:147], v[200:203], 0
	v_mfma_f32_16x16x32_bf16 v[0:3], v[152:155], v[200:203], 0
	v_mfma_f32_16x16x32_bf16 v[52:55], v[148:151], v[164:167], v[52:55]
	v_mfma_f32_16x16x32_bf16 v[48:51], v[156:159], v[164:167], v[48:51]
	v_mfma_f32_16x16x32_bf16 v[36:39], v[148:151], v[172:175], v[36:39]
	v_mfma_f32_16x16x32_bf16 v[32:35], v[156:159], v[172:175], v[32:35]
	v_mfma_f32_16x16x32_bf16 v[20:23], v[148:151], v[196:199], v[20:23]
	v_mfma_f32_16x16x32_bf16 v[16:19], v[156:159], v[196:199], v[16:19]
	v_mfma_f32_16x16x32_bf16 v[4:7], v[148:151], v[204:207], v[4:7]
	v_mfma_f32_16x16x32_bf16 v[0:3], v[156:159], v[204:207], v[0:3]
	s_barrier
	s_add_i32 s59, 0, 0x18000
	s_add_i32 s60, 0, 0x1c000
	v_add_u32_e32 v140, s59, v214
	v_add_u32_e32 v156, s60, v214
	ds_read_b128 v[128:131], v140
	ds_read_b128 v[132:135], v140 offset:1024
	ds_read_b128 v[136:139], v140 offset:2048
	ds_read_b128 v[140:143], v140 offset:3072
	ds_read_b128 v[144:147], v156
	ds_read_b128 v[148:151], v156 offset:1024
	ds_read_b128 v[152:155], v156 offset:2048
	ds_read_b128 v[156:159], v156 offset:3072
	s_add_u32 s46, s46, 0x80000
	s_addc_u32 s47, s47, 0
	s_mov_b32 m0, s49
	ds_read_b128 v[160:163], v218 offset:32768
	ds_read_b128 v[164:167], v218 offset:33792
	ds_read_b128 v[168:171], v218 offset:34816
	ds_read_b128 v[172:175], v218 offset:35840
	ds_read_b128 v[192:195], v218 offset:36864
	ds_read_b128 v[196:199], v218 offset:37888
	ds_read_b128 v[200:203], v218 offset:38912
	ds_read_b128 v[204:207], v218 offset:39936
	global_load_lds_dwordx4 v176, s[46:47]
	s_mov_b32 m0, s50
	s_nop 0
	global_load_lds_dwordx4 v180, s[46:47]
	s_waitcnt vmcnt(8)
	s_waitcnt lgkmcnt(0)
	s_barrier
	v_mfma_f32_16x16x32_bf16 v[124:127], v[128:131], v[160:163], v[124:127]
	v_mfma_f32_16x16x32_bf16 v[120:123], v[136:139], v[160:163], v[120:123]
	v_mfma_f32_16x16x32_bf16 v[108:111], v[128:131], v[168:171], v[108:111]
	v_mfma_f32_16x16x32_bf16 v[104:107], v[136:139], v[168:171], v[104:107]
	v_mfma_f32_16x16x32_bf16 v[92:95], v[128:131], v[192:195], v[92:95]
	v_mfma_f32_16x16x32_bf16 v[88:91], v[136:139], v[192:195], v[88:91]
	v_mfma_f32_16x16x32_bf16 v[76:79], v[128:131], v[200:203], v[76:79]
	v_mfma_f32_16x16x32_bf16 v[72:75], v[136:139], v[200:203], v[72:75]
	v_mfma_f32_16x16x32_bf16 v[124:127], v[132:135], v[164:167], v[124:127]
	v_mfma_f32_16x16x32_bf16 v[120:123], v[140:143], v[164:167], v[120:123]
	v_mfma_f32_16x16x32_bf16 v[108:111], v[132:135], v[172:175], v[108:111]
	v_mfma_f32_16x16x32_bf16 v[104:107], v[140:143], v[172:175], v[104:107]
	v_mfma_f32_16x16x32_bf16 v[92:95], v[132:135], v[196:199], v[92:95]
	v_mfma_f32_16x16x32_bf16 v[88:91], v[140:143], v[196:199], v[88:91]
	v_mfma_f32_16x16x32_bf16 v[76:79], v[132:135], v[204:207], v[76:79]
	v_mfma_f32_16x16x32_bf16 v[72:75], v[140:143], v[204:207], v[72:75]
	v_mfma_f32_16x16x32_bf16 v[116:119], v[144:147], v[160:163], v[116:119]
	v_mfma_f32_16x16x32_bf16 v[112:115], v[152:155], v[160:163], v[112:115]
	v_mfma_f32_16x16x32_bf16 v[100:103], v[144:147], v[168:171], v[100:103]
	v_mfma_f32_16x16x32_bf16 v[96:99], v[152:155], v[168:171], v[96:99]
	v_mfma_f32_16x16x32_bf16 v[84:87], v[144:147], v[192:195], v[84:87]
	v_mfma_f32_16x16x32_bf16 v[80:83], v[152:155], v[192:195], v[80:83]
	v_mfma_f32_16x16x32_bf16 v[68:71], v[144:147], v[200:203], v[68:71]
	v_mfma_f32_16x16x32_bf16 v[64:67], v[152:155], v[200:203], v[64:67]
	v_mfma_f32_16x16x32_bf16 v[116:119], v[148:151], v[164:167], v[116:119]
	v_mfma_f32_16x16x32_bf16 v[112:115], v[156:159], v[164:167], v[112:115]
	v_mfma_f32_16x16x32_bf16 v[100:103], v[148:151], v[172:175], v[100:103]
	v_mfma_f32_16x16x32_bf16 v[96:99], v[156:159], v[172:175], v[96:99]
	v_mfma_f32_16x16x32_bf16 v[84:87], v[148:151], v[196:199], v[84:87]
	v_mfma_f32_16x16x32_bf16 v[80:83], v[156:159], v[196:199], v[80:83]
	v_mfma_f32_16x16x32_bf16 v[68:71], v[148:151], v[204:207], v[68:71]
	v_mfma_f32_16x16x32_bf16 v[64:67], v[156:159], v[204:207], v[64:67]
	s_barrier
	s_add_i32 s46, s59, s31
	s_mov_b32 m0, s46
	ds_read_b128 v[160:163], v218 offset:49152
	ds_read_b128 v[164:167], v218 offset:50176
	ds_read_b128 v[168:171], v218 offset:51200
	ds_read_b128 v[172:175], v218 offset:52224
	ds_read_b128 v[192:195], v218 offset:53248
	ds_read_b128 v[196:199], v218 offset:54272
	ds_read_b128 v[200:203], v218 offset:55296
	ds_read_b128 v[204:207], v218 offset:56320
	global_load_lds_dwordx4 v178, s[98:99]
	s_add_i32 m0, s46, 0x2000
	s_add_u32 s44, s44, 0x80080
	s_addc_u32 s45, s45, 0
	s_add_i32 s46, s60, s31
	global_load_lds_dwordx4 v182, s[98:99]
	s_mov_b32 m0, s46
	s_nop 0
	global_load_lds_dwordx4 v178, s[44:45]
	s_add_i32 m0, s46, 0x2000
	s_nop 0
	global_load_lds_dwordx4 v182, s[44:45]
	s_mov_b32 m0, s52
	s_nop 0
	global_load_lds_dwordx4 v176, s[100:101]
	s_mov_b32 m0, s53
	s_nop 0
	global_load_lds_dwordx4 v180, s[100:101]
	s_waitcnt vmcnt(8)
	s_waitcnt lgkmcnt(0)
	s_barrier
	v_mfma_f32_16x16x32_bf16 v[60:63], v[128:131], v[160:163], v[60:63]
	v_mfma_f32_16x16x32_bf16 v[56:59], v[136:139], v[160:163], v[56:59]
	v_mfma_f32_16x16x32_bf16 v[44:47], v[128:131], v[168:171], v[44:47]
	v_mfma_f32_16x16x32_bf16 v[40:43], v[136:139], v[168:171], v[40:43]
	v_mfma_f32_16x16x32_bf16 v[28:31], v[128:131], v[192:195], v[28:31]
	v_mfma_f32_16x16x32_bf16 v[24:27], v[136:139], v[192:195], v[24:27]
	v_mfma_f32_16x16x32_bf16 v[12:15], v[128:131], v[200:203], v[12:15]
	v_mfma_f32_16x16x32_bf16 v[8:11], v[136:139], v[200:203], v[8:11]
	v_mfma_f32_16x16x32_bf16 v[60:63], v[132:135], v[164:167], v[60:63]
	v_mfma_f32_16x16x32_bf16 v[56:59], v[140:143], v[164:167], v[56:59]
	v_mfma_f32_16x16x32_bf16 v[44:47], v[132:135], v[172:175], v[44:47]
	v_mfma_f32_16x16x32_bf16 v[40:43], v[140:143], v[172:175], v[40:43]
	v_mfma_f32_16x16x32_bf16 v[28:31], v[132:135], v[196:199], v[28:31]
	v_mfma_f32_16x16x32_bf16 v[24:27], v[140:143], v[196:199], v[24:27]
	v_mfma_f32_16x16x32_bf16 v[12:15], v[132:135], v[204:207], v[12:15]
	v_mfma_f32_16x16x32_bf16 v[8:11], v[140:143], v[204:207], v[8:11]
	v_mfma_f32_16x16x32_bf16 v[52:55], v[144:147], v[160:163], v[52:55]
	v_mfma_f32_16x16x32_bf16 v[48:51], v[152:155], v[160:163], v[48:51]
	v_mfma_f32_16x16x32_bf16 v[36:39], v[144:147], v[168:171], v[36:39]
	v_mfma_f32_16x16x32_bf16 v[32:35], v[152:155], v[168:171], v[32:35]
	v_mfma_f32_16x16x32_bf16 v[20:23], v[144:147], v[192:195], v[20:23]
	v_mfma_f32_16x16x32_bf16 v[16:19], v[152:155], v[192:195], v[16:19]
	v_mfma_f32_16x16x32_bf16 v[4:7], v[144:147], v[200:203], v[4:7]
	v_mfma_f32_16x16x32_bf16 v[0:3], v[152:155], v[200:203], v[0:3]
	v_mfma_f32_16x16x32_bf16 v[52:55], v[148:151], v[164:167], v[52:55]
	v_mfma_f32_16x16x32_bf16 v[48:51], v[156:159], v[164:167], v[48:51]
	v_mfma_f32_16x16x32_bf16 v[36:39], v[148:151], v[172:175], v[36:39]
	v_mfma_f32_16x16x32_bf16 v[32:35], v[156:159], v[172:175], v[32:35]
	v_mfma_f32_16x16x32_bf16 v[20:23], v[148:151], v[196:199], v[20:23]
	v_mfma_f32_16x16x32_bf16 v[16:19], v[156:159], v[196:199], v[16:19]
	v_mfma_f32_16x16x32_bf16 v[4:7], v[148:151], v[204:207], v[4:7]
	v_mfma_f32_16x16x32_bf16 v[0:3], v[156:159], v[204:207], v[0:3]
	s_barrier
	s_add_i32 s58, s58, 2
	s_add_u32 s42, s42, 0x100
	s_addc_u32 s43, s43, 0
	s_add_u32 s25, s25, 0x100
	s_addc_u32 s35, s35, 0
	s_cmp_gt_u32 s58, 29
.LBB0_543:
	ds_read_b128 v[128:131], v216
	ds_read_b128 v[132:135], v216 offset:1024
	ds_read_b128 v[136:139], v216 offset:2048
	ds_read_b128 v[140:143], v216 offset:3072
	ds_read_b128 v[144:147], v217
	ds_read_b128 v[148:151], v217 offset:1024
	ds_read_b128 v[152:155], v217 offset:2048
	ds_read_b128 v[156:159], v217 offset:3072
	s_add_u32 s44, s42, 0xfff80080
	s_addc_u32 s45, s43, -1
	s_cmp_eq_u32 s58, 28
	s_cselect_b32 s47, s0, s45
	s_cselect_b32 s46, s1, s44
	s_cselect_b32 s45, s3, s35
	s_cselect_b32 s44, s9, s25
	s_add_i32 m0, s41, 0xc000
	ds_read_b128 v[160:163], v218
	ds_read_b128 v[164:167], v218 offset:1024
	ds_read_b128 v[168:171], v218 offset:2048
	ds_read_b128 v[172:175], v218 offset:3072
	ds_read_b128 v[192:195], v218 offset:4096
	ds_read_b128 v[196:199], v218 offset:5120
	ds_read_b128 v[200:203], v218 offset:6144
	ds_read_b128 v[204:207], v218 offset:7168
	global_load_lds_dwordx4 v184, s[42:43]
	s_add_i32 m0, s41, 0xe000
	s_nop 0
	global_load_lds_dwordx4 v186, s[42:43]
	s_waitcnt vmcnt(8)
	s_waitcnt lgkmcnt(0)
	s_barrier
	v_mfma_f32_16x16x32_bf16 v[124:127], v[128:131], v[160:163], v[124:127]
	v_mfma_f32_16x16x32_bf16 v[120:123], v[136:139], v[160:163], v[120:123]
	v_mfma_f32_16x16x32_bf16 v[108:111], v[128:131], v[168:171], v[108:111]
	v_mfma_f32_16x16x32_bf16 v[104:107], v[136:139], v[168:171], v[104:107]
	v_mfma_f32_16x16x32_bf16 v[92:95], v[128:131], v[192:195], v[92:95]
	v_mfma_f32_16x16x32_bf16 v[88:91], v[136:139], v[192:195], v[88:91]
	v_mfma_f32_16x16x32_bf16 v[76:79], v[128:131], v[200:203], v[76:79]
	v_mfma_f32_16x16x32_bf16 v[72:75], v[136:139], v[200:203], v[72:75]
	v_mfma_f32_16x16x32_bf16 v[124:127], v[132:135], v[164:167], v[124:127]
	v_mfma_f32_16x16x32_bf16 v[120:123], v[140:143], v[164:167], v[120:123]
	v_mfma_f32_16x16x32_bf16 v[108:111], v[132:135], v[172:175], v[108:111]
	v_mfma_f32_16x16x32_bf16 v[104:107], v[140:143], v[172:175], v[104:107]
	v_mfma_f32_16x16x32_bf16 v[92:95], v[132:135], v[196:199], v[92:95]
	v_mfma_f32_16x16x32_bf16 v[88:91], v[140:143], v[196:199], v[88:91]
	v_mfma_f32_16x16x32_bf16 v[76:79], v[132:135], v[204:207], v[76:79]
	v_mfma_f32_16x16x32_bf16 v[72:75], v[140:143], v[204:207], v[72:75]
	v_mfma_f32_16x16x32_bf16 v[116:119], v[144:147], v[160:163], v[116:119]
	v_mfma_f32_16x16x32_bf16 v[112:115], v[152:155], v[160:163], v[112:115]
	v_mfma_f32_16x16x32_bf16 v[100:103], v[144:147], v[168:171], v[100:103]
	v_mfma_f32_16x16x32_bf16 v[96:99], v[152:155], v[168:171], v[96:99]
	v_mfma_f32_16x16x32_bf16 v[84:87], v[144:147], v[192:195], v[84:87]
	v_mfma_f32_16x16x32_bf16 v[80:83], v[152:155], v[192:195], v[80:83]
	v_mfma_f32_16x16x32_bf16 v[68:71], v[144:147], v[200:203], v[68:71]
	v_mfma_f32_16x16x32_bf16 v[64:67], v[152:155], v[200:203], v[64:67]
	v_mfma_f32_16x16x32_bf16 v[116:119], v[148:151], v[164:167], v[116:119]
	v_mfma_f32_16x16x32_bf16 v[112:115], v[156:159], v[164:167], v[112:115]
	v_mfma_f32_16x16x32_bf16 v[100:103], v[148:151], v[172:175], v[100:103]
	v_mfma_f32_16x16x32_bf16 v[96:99], v[156:159], v[172:175], v[96:99]
	v_mfma_f32_16x16x32_bf16 v[84:87], v[148:151], v[196:199], v[84:87]
	v_mfma_f32_16x16x32_bf16 v[80:83], v[156:159], v[196:199], v[80:83]
	v_mfma_f32_16x16x32_bf16 v[68:71], v[148:151], v[204:207], v[68:71]
	v_mfma_f32_16x16x32_bf16 v[64:67], v[156:159], v[204:207], v[64:67]
	s_barrier
	s_add_i32 s59, s55, s31
	s_add_u32 s98, s44, s20
	s_addc_u32 s99, s45, s21
	s_mov_b32 m0, s59
	ds_read_b128 v[160:163], v218 offset:16384
	ds_read_b128 v[164:167], v218 offset:17408
	ds_read_b128 v[168:171], v218 offset:18432
	ds_read_b128 v[172:175], v218 offset:19456
	ds_read_b128 v[192:195], v218 offset:20480
	ds_read_b128 v[196:199], v218 offset:21504
	ds_read_b128 v[200:203], v218 offset:22528
	ds_read_b128 v[204:207], v218 offset:23552
	global_load_lds_dwordx4 v178, s[44:45]
	s_add_i32 m0, s59, 0x2000
	s_add_u32 s60, s44, 0x80000
	s_addc_u32 s61, s45, 0
	s_add_i32 s59, s56, s31
	global_load_lds_dwordx4 v182, s[44:45]
	s_mov_b32 m0, s59
	s_add_u32 s100, s46, s20
	s_addc_u32 s101, s47, s21
	global_load_lds_dwordx4 v178, s[60:61]
	s_add_i32 m0, s59, 0x2000
	s_nop 0
	global_load_lds_dwordx4 v182, s[60:61]
	s_mov_b32 m0, s41
	s_nop 0
	global_load_lds_dwordx4 v176, s[46:47]
	s_mov_b32 m0, s48
	s_nop 0
	global_load_lds_dwordx4 v180, s[46:47]
	s_waitcnt vmcnt(8)
	s_waitcnt lgkmcnt(0)
	s_barrier
	v_mfma_f32_16x16x32_bf16 v[60:63], v[128:131], v[160:163], v[60:63]
	v_mfma_f32_16x16x32_bf16 v[56:59], v[136:139], v[160:163], v[56:59]
	v_mfma_f32_16x16x32_bf16 v[44:47], v[128:131], v[168:171], v[44:47]
	v_mfma_f32_16x16x32_bf16 v[40:43], v[136:139], v[168:171], v[40:43]
	v_mfma_f32_16x16x32_bf16 v[28:31], v[128:131], v[192:195], v[28:31]
	v_mfma_f32_16x16x32_bf16 v[24:27], v[136:139], v[192:195], v[24:27]
	v_mfma_f32_16x16x32_bf16 v[12:15], v[128:131], v[200:203], v[12:15]
	v_mfma_f32_16x16x32_bf16 v[8:11], v[136:139], v[200:203], v[8:11]
	v_mfma_f32_16x16x32_bf16 v[60:63], v[132:135], v[164:167], v[60:63]
	v_mfma_f32_16x16x32_bf16 v[56:59], v[140:143], v[164:167], v[56:59]
	v_mfma_f32_16x16x32_bf16 v[44:47], v[132:135], v[172:175], v[44:47]
	v_mfma_f32_16x16x32_bf16 v[40:43], v[140:143], v[172:175], v[40:43]
	v_mfma_f32_16x16x32_bf16 v[28:31], v[132:135], v[196:199], v[28:31]
	v_mfma_f32_16x16x32_bf16 v[24:27], v[140:143], v[196:199], v[24:27]
	v_mfma_f32_16x16x32_bf16 v[12:15], v[132:135], v[204:207], v[12:15]
	v_mfma_f32_16x16x32_bf16 v[8:11], v[140:143], v[204:207], v[8:11]
	v_mfma_f32_16x16x32_bf16 v[52:55], v[144:147], v[160:163], v[52:55]
	v_mfma_f32_16x16x32_bf16 v[48:51], v[152:155], v[160:163], v[48:51]
	v_mfma_f32_16x16x32_bf16 v[36:39], v[144:147], v[168:171], v[36:39]
	v_mfma_f32_16x16x32_bf16 v[32:35], v[152:155], v[168:171], v[32:35]
	v_mfma_f32_16x16x32_bf16 v[20:23], v[144:147], v[192:195], v[20:23]
	v_mfma_f32_16x16x32_bf16 v[16:19], v[152:155], v[192:195], v[16:19]
	v_mfma_f32_16x16x32_bf16 v[4:7], v[144:147], v[200:203], v[4:7]
	v_mfma_f32_16x16x32_bf16 v[0:3], v[152:155], v[200:203], v[0:3]
	v_mfma_f32_16x16x32_bf16 v[52:55], v[148:151], v[164:167], v[52:55]
	v_mfma_f32_16x16x32_bf16 v[48:51], v[156:159], v[164:167], v[48:51]
	v_mfma_f32_16x16x32_bf16 v[36:39], v[148:151], v[172:175], v[36:39]
	v_mfma_f32_16x16x32_bf16 v[32:35], v[156:159], v[172:175], v[32:35]
	v_mfma_f32_16x16x32_bf16 v[20:23], v[148:151], v[196:199], v[20:23]
	v_mfma_f32_16x16x32_bf16 v[16:19], v[156:159], v[196:199], v[16:19]
	v_mfma_f32_16x16x32_bf16 v[4:7], v[148:151], v[204:207], v[4:7]
	v_mfma_f32_16x16x32_bf16 v[0:3], v[156:159], v[204:207], v[0:3]
	s_barrier
	s_add_i32 s59, 0, 0x18000
	s_add_i32 s60, 0, 0x1c000
	v_add_u32_e32 v140, s59, v214
	v_add_u32_e32 v156, s60, v214
	ds_read_b128 v[128:131], v140
	ds_read_b128 v[132:135], v140 offset:1024
	ds_read_b128 v[136:139], v140 offset:2048
	ds_read_b128 v[140:143], v140 offset:3072
	ds_read_b128 v[144:147], v156
	ds_read_b128 v[148:151], v156 offset:1024
	ds_read_b128 v[152:155], v156 offset:2048
	ds_read_b128 v[156:159], v156 offset:3072
	s_add_u32 s46, s46, 0x80000
	s_addc_u32 s47, s47, 0
	s_mov_b32 m0, s49
	ds_read_b128 v[160:163], v218 offset:32768
	ds_read_b128 v[164:167], v218 offset:33792
	ds_read_b128 v[168:171], v218 offset:34816
	ds_read_b128 v[172:175], v218 offset:35840
	ds_read_b128 v[192:195], v218 offset:36864
	ds_read_b128 v[196:199], v218 offset:37888
	ds_read_b128 v[200:203], v218 offset:38912
	ds_read_b128 v[204:207], v218 offset:39936
	global_load_lds_dwordx4 v176, s[46:47]
	s_mov_b32 m0, s50
	s_nop 0
	global_load_lds_dwordx4 v180, s[46:47]
	s_waitcnt vmcnt(8)
	s_waitcnt lgkmcnt(0)
	s_barrier
	v_mfma_f32_16x16x32_bf16 v[124:127], v[128:131], v[160:163], v[124:127]
	v_mfma_f32_16x16x32_bf16 v[120:123], v[136:139], v[160:163], v[120:123]
	v_mfma_f32_16x16x32_bf16 v[108:111], v[128:131], v[168:171], v[108:111]
	v_mfma_f32_16x16x32_bf16 v[104:107], v[136:139], v[168:171], v[104:107]
	v_mfma_f32_16x16x32_bf16 v[92:95], v[128:131], v[192:195], v[92:95]
	v_mfma_f32_16x16x32_bf16 v[88:91], v[136:139], v[192:195], v[88:91]
	v_mfma_f32_16x16x32_bf16 v[76:79], v[128:131], v[200:203], v[76:79]
	v_mfma_f32_16x16x32_bf16 v[72:75], v[136:139], v[200:203], v[72:75]
	v_mfma_f32_16x16x32_bf16 v[124:127], v[132:135], v[164:167], v[124:127]
	v_mfma_f32_16x16x32_bf16 v[120:123], v[140:143], v[164:167], v[120:123]
	v_mfma_f32_16x16x32_bf16 v[108:111], v[132:135], v[172:175], v[108:111]
	v_mfma_f32_16x16x32_bf16 v[104:107], v[140:143], v[172:175], v[104:107]
	v_mfma_f32_16x16x32_bf16 v[92:95], v[132:135], v[196:199], v[92:95]
	v_mfma_f32_16x16x32_bf16 v[88:91], v[140:143], v[196:199], v[88:91]
	v_mfma_f32_16x16x32_bf16 v[76:79], v[132:135], v[204:207], v[76:79]
	v_mfma_f32_16x16x32_bf16 v[72:75], v[140:143], v[204:207], v[72:75]
	v_mfma_f32_16x16x32_bf16 v[116:119], v[144:147], v[160:163], v[116:119]
	v_mfma_f32_16x16x32_bf16 v[112:115], v[152:155], v[160:163], v[112:115]
	v_mfma_f32_16x16x32_bf16 v[100:103], v[144:147], v[168:171], v[100:103]
	v_mfma_f32_16x16x32_bf16 v[96:99], v[152:155], v[168:171], v[96:99]
	v_mfma_f32_16x16x32_bf16 v[84:87], v[144:147], v[192:195], v[84:87]
	v_mfma_f32_16x16x32_bf16 v[80:83], v[152:155], v[192:195], v[80:83]
	v_mfma_f32_16x16x32_bf16 v[68:71], v[144:147], v[200:203], v[68:71]
	v_mfma_f32_16x16x32_bf16 v[64:67], v[152:155], v[200:203], v[64:67]
	v_mfma_f32_16x16x32_bf16 v[116:119], v[148:151], v[164:167], v[116:119]
	v_mfma_f32_16x16x32_bf16 v[112:115], v[156:159], v[164:167], v[112:115]
	v_mfma_f32_16x16x32_bf16 v[100:103], v[148:151], v[172:175], v[100:103]
	v_mfma_f32_16x16x32_bf16 v[96:99], v[156:159], v[172:175], v[96:99]
	v_mfma_f32_16x16x32_bf16 v[84:87], v[148:151], v[196:199], v[84:87]
	v_mfma_f32_16x16x32_bf16 v[80:83], v[156:159], v[196:199], v[80:83]
	v_mfma_f32_16x16x32_bf16 v[68:71], v[148:151], v[204:207], v[68:71]
	v_mfma_f32_16x16x32_bf16 v[64:67], v[156:159], v[204:207], v[64:67]
	s_barrier
	s_add_i32 s46, s59, s31
	s_mov_b32 m0, s46
	ds_read_b128 v[160:163], v218 offset:49152
	ds_read_b128 v[164:167], v218 offset:50176
	ds_read_b128 v[168:171], v218 offset:51200
	ds_read_b128 v[172:175], v218 offset:52224
	ds_read_b128 v[192:195], v218 offset:53248
	ds_read_b128 v[196:199], v218 offset:54272
	ds_read_b128 v[200:203], v218 offset:55296
	ds_read_b128 v[204:207], v218 offset:56320
	global_load_lds_dwordx4 v178, s[98:99]
	s_add_i32 m0, s46, 0x2000
	s_add_u32 s44, s44, 0x80080
	s_addc_u32 s45, s45, 0
	s_add_i32 s46, s60, s31
	global_load_lds_dwordx4 v182, s[98:99]
	s_mov_b32 m0, s46
	s_nop 0
	global_load_lds_dwordx4 v178, s[44:45]
	s_add_i32 m0, s46, 0x2000
	s_nop 0
	global_load_lds_dwordx4 v182, s[44:45]
	s_mov_b32 m0, s52
	s_nop 0
	global_load_lds_dwordx4 v176, s[100:101]
	s_mov_b32 m0, s53
	s_nop 0
	global_load_lds_dwordx4 v180, s[100:101]
	s_waitcnt vmcnt(8)
	s_waitcnt lgkmcnt(0)
	s_barrier
	v_mfma_f32_16x16x32_bf16 v[60:63], v[128:131], v[160:163], v[60:63]
	v_mfma_f32_16x16x32_bf16 v[56:59], v[136:139], v[160:163], v[56:59]
	v_mfma_f32_16x16x32_bf16 v[44:47], v[128:131], v[168:171], v[44:47]
	v_mfma_f32_16x16x32_bf16 v[40:43], v[136:139], v[168:171], v[40:43]
	v_mfma_f32_16x16x32_bf16 v[28:31], v[128:131], v[192:195], v[28:31]
	v_mfma_f32_16x16x32_bf16 v[24:27], v[136:139], v[192:195], v[24:27]
	v_mfma_f32_16x16x32_bf16 v[12:15], v[128:131], v[200:203], v[12:15]
	v_mfma_f32_16x16x32_bf16 v[8:11], v[136:139], v[200:203], v[8:11]
	v_mfma_f32_16x16x32_bf16 v[60:63], v[132:135], v[164:167], v[60:63]
	v_mfma_f32_16x16x32_bf16 v[56:59], v[140:143], v[164:167], v[56:59]
	v_mfma_f32_16x16x32_bf16 v[44:47], v[132:135], v[172:175], v[44:47]
	v_mfma_f32_16x16x32_bf16 v[40:43], v[140:143], v[172:175], v[40:43]
	v_mfma_f32_16x16x32_bf16 v[28:31], v[132:135], v[196:199], v[28:31]
	v_mfma_f32_16x16x32_bf16 v[24:27], v[140:143], v[196:199], v[24:27]
	v_mfma_f32_16x16x32_bf16 v[12:15], v[132:135], v[204:207], v[12:15]
	v_mfma_f32_16x16x32_bf16 v[8:11], v[140:143], v[204:207], v[8:11]
	v_mfma_f32_16x16x32_bf16 v[52:55], v[144:147], v[160:163], v[52:55]
	v_mfma_f32_16x16x32_bf16 v[48:51], v[152:155], v[160:163], v[48:51]
	v_mfma_f32_16x16x32_bf16 v[36:39], v[144:147], v[168:171], v[36:39]
	v_mfma_f32_16x16x32_bf16 v[32:35], v[152:155], v[168:171], v[32:35]
	v_mfma_f32_16x16x32_bf16 v[20:23], v[144:147], v[192:195], v[20:23]
	v_mfma_f32_16x16x32_bf16 v[16:19], v[152:155], v[192:195], v[16:19]
	v_mfma_f32_16x16x32_bf16 v[4:7], v[144:147], v[200:203], v[4:7]
	v_mfma_f32_16x16x32_bf16 v[0:3], v[152:155], v[200:203], v[0:3]
	v_mfma_f32_16x16x32_bf16 v[52:55], v[148:151], v[164:167], v[52:55]
	v_mfma_f32_16x16x32_bf16 v[48:51], v[156:159], v[164:167], v[48:51]
	v_mfma_f32_16x16x32_bf16 v[36:39], v[148:151], v[172:175], v[36:39]
	v_mfma_f32_16x16x32_bf16 v[32:35], v[156:159], v[172:175], v[32:35]
	v_mfma_f32_16x16x32_bf16 v[20:23], v[148:151], v[196:199], v[20:23]
	v_mfma_f32_16x16x32_bf16 v[16:19], v[156:159], v[196:199], v[16:19]
	v_mfma_f32_16x16x32_bf16 v[4:7], v[148:151], v[204:207], v[4:7]
	v_mfma_f32_16x16x32_bf16 v[0:3], v[156:159], v[204:207], v[0:3]
	s_barrier
	s_add_i32 s58, s58, 2
	s_add_u32 s42, s42, 0x100
	s_addc_u32 s43, s43, 0
	s_add_u32 s25, s25, 0x100
	s_addc_u32 s35, s35, 0
	s_cmp_gt_u32 s58, 29
	s_cbranch_scc0 .LBB0_543
	s_and_b64 vcc, exec, s[22:23]
	s_cbranch_vccz .LBB0_546
	s_barrier

.LBB0_635:
	s_ashr_i32 s67, s66, 31
	s_lshl_b64 s[12:13], s[66:67], 20
	s_add_u32 s70, s55, s12
	s_addc_u32 s71, s57, s13
	s_and_b64 s[6:7], s[6:7], exec
	s_cselect_b32 s1, s71, s11
	s_cselect_b32 s3, s70, s10
	s_add_u32 s6, s8, 0x80080
	s_addc_u32 s7, s9, 0
	s_add_u32 s12, s10, 0x100
	s_addc_u32 s13, s11, 0
	s_mov_b32 s15, -2
	s_waitcnt vmcnt(0)
	ds_read_b128 v[148:151], v197
	ds_read_b128 v[170:173], v197 offset:1024
	ds_read_b128 v[174:177], v197 offset:2048
	ds_read_b128 v[178:181], v197 offset:3072
	ds_read_b128 v[182:185], v198
	ds_read_b128 v[186:189], v198 offset:1024
	ds_read_b128 v[202:205], v198 offset:2048
	ds_read_b128 v[206:209], v198 offset:3072
	s_add_u32 s8, s6, 0xfff80080
	s_addc_u32 s9, s7, -1
	s_cmp_eq_u32 s15, 28
	s_cselect_b32 s11, s69, s9
	s_cselect_b32 s10, s68, s8
	s_cselect_b32 s9, s1, s13
	s_cselect_b32 s8, s3, s12
	s_add_i32 m0, s72, 0xc000
	ds_read_b128 v[214:217], v199
	ds_read_b128 v[218:221], v199 offset:1024
	ds_read_b128 v[222:225], v199 offset:2048
	ds_read_b128 v[226:229], v199 offset:3072
	ds_read_b128 v[230:233], v199 offset:4096
	ds_read_b128 v[234:237], v199 offset:5120
	ds_read_b128 v[238:241], v199 offset:6144
	ds_read_b128 v[242:245], v199 offset:7168
	global_load_lds_dwordx4 v162, s[6:7]
	s_add_i32 m0, s72, 0xe000
	s_nop 0
	global_load_lds_dwordx4 v164, s[6:7]
	s_waitcnt vmcnt(8)
	s_waitcnt lgkmcnt(0)
	s_barrier
	v_mfma_f32_16x16x32_bf16 v[112:115], v[148:151], v[214:217], 0
	v_mfma_f32_16x16x32_bf16 v[80:83], v[174:177], v[214:217], 0
	v_mfma_f32_16x16x32_bf16 v[116:119], v[148:151], v[222:225], 0
	v_mfma_f32_16x16x32_bf16 v[88:91], v[174:177], v[222:225], 0
	v_mfma_f32_16x16x32_bf16 v[124:127], v[148:151], v[230:233], 0
	v_mfma_f32_16x16x32_bf16 v[92:95], v[174:177], v[230:233], 0
	v_mfma_f32_16x16x32_bf16 v[120:123], v[148:151], v[238:241], 0
	v_mfma_f32_16x16x32_bf16 v[84:87], v[174:177], v[238:241], 0
	v_mfma_f32_16x16x32_bf16 v[112:115], v[170:173], v[218:221], v[112:115]
	v_mfma_f32_16x16x32_bf16 v[80:83], v[178:181], v[218:221], v[80:83]
	v_mfma_f32_16x16x32_bf16 v[116:119], v[170:173], v[226:229], v[116:119]
	v_mfma_f32_16x16x32_bf16 v[88:91], v[178:181], v[226:229], v[88:91]
	v_mfma_f32_16x16x32_bf16 v[124:127], v[170:173], v[234:237], v[124:127]
	v_mfma_f32_16x16x32_bf16 v[92:95], v[178:181], v[234:237], v[92:95]
	v_mfma_f32_16x16x32_bf16 v[120:123], v[170:173], v[242:245], v[120:123]
	v_mfma_f32_16x16x32_bf16 v[84:87], v[178:181], v[242:245], v[84:87]
	v_mfma_f32_16x16x32_bf16 v[108:111], v[182:185], v[214:217], 0
	v_mfma_f32_16x16x32_bf16 v[76:79], v[202:205], v[214:217], 0
	v_mfma_f32_16x16x32_bf16 v[104:107], v[182:185], v[222:225], 0
	v_mfma_f32_16x16x32_bf16 v[72:75], v[202:205], v[222:225], 0
	v_mfma_f32_16x16x32_bf16 v[100:103], v[182:185], v[230:233], 0
	v_mfma_f32_16x16x32_bf16 v[68:71], v[202:205], v[230:233], 0
	v_mfma_f32_16x16x32_bf16 v[96:99], v[182:185], v[238:241], 0
	v_mfma_f32_16x16x32_bf16 v[64:67], v[202:205], v[238:241], 0
	v_mfma_f32_16x16x32_bf16 v[108:111], v[186:189], v[218:221], v[108:111]
	v_mfma_f32_16x16x32_bf16 v[76:79], v[206:209], v[218:221], v[76:79]
	v_mfma_f32_16x16x32_bf16 v[104:107], v[186:189], v[226:229], v[104:107]
	v_mfma_f32_16x16x32_bf16 v[72:75], v[206:209], v[226:229], v[72:75]
	v_mfma_f32_16x16x32_bf16 v[100:103], v[186:189], v[234:237], v[100:103]
	v_mfma_f32_16x16x32_bf16 v[68:71], v[206:209], v[234:237], v[68:71]
	v_mfma_f32_16x16x32_bf16 v[96:99], v[186:189], v[242:245], v[96:99]
	v_mfma_f32_16x16x32_bf16 v[64:67], v[206:209], v[242:245], v[64:67]
	s_barrier
	s_add_i32 s16, s94, s63
	s_add_u32 s98, s8, s40
	s_addc_u32 s99, s9, s41
	s_mov_b32 m0, s16
	ds_read_b128 v[214:217], v199 offset:16384
	ds_read_b128 v[218:221], v199 offset:17408
	ds_read_b128 v[222:225], v199 offset:18432
	ds_read_b128 v[226:229], v199 offset:19456
	ds_read_b128 v[230:233], v199 offset:20480
	ds_read_b128 v[234:237], v199 offset:21504
	ds_read_b128 v[238:241], v199 offset:22528
	ds_read_b128 v[242:245], v199 offset:23552
	global_load_lds_dwordx4 v154, s[8:9]
	s_add_i32 m0, s16, 0x2000
	s_add_u32 s16, s8, 0x80000
	s_addc_u32 s17, s9, 0
	s_add_i32 s18, s95, s63
	global_load_lds_dwordx4 v158, s[8:9]
	s_mov_b32 m0, s18
	s_add_u32 s100, s10, s40
	s_addc_u32 s101, s11, s41
	global_load_lds_dwordx4 v154, s[16:17]
	s_add_i32 m0, s18, 0x2000
	s_nop 0
	global_load_lds_dwordx4 v158, s[16:17]
	s_mov_b32 m0, s72
	s_nop 0
	global_load_lds_dwordx4 v152, s[10:11]
	s_mov_b32 m0, s73
	s_nop 0
	global_load_lds_dwordx4 v156, s[10:11]
	s_waitcnt vmcnt(8)
	s_waitcnt lgkmcnt(0)
	s_barrier
	v_mfma_f32_16x16x32_bf16 v[48:51], v[148:151], v[214:217], 0
	v_mfma_f32_16x16x32_bf16 v[16:19], v[174:177], v[214:217], 0
	v_mfma_f32_16x16x32_bf16 v[52:55], v[148:151], v[222:225], 0
	v_mfma_f32_16x16x32_bf16 v[24:27], v[174:177], v[222:225], 0
	v_mfma_f32_16x16x32_bf16 v[60:63], v[148:151], v[230:233], 0
	v_mfma_f32_16x16x32_bf16 v[28:31], v[174:177], v[230:233], 0
	v_mfma_f32_16x16x32_bf16 v[56:59], v[148:151], v[238:241], 0
	v_mfma_f32_16x16x32_bf16 v[20:23], v[174:177], v[238:241], 0
	v_mfma_f32_16x16x32_bf16 v[48:51], v[170:173], v[218:221], v[48:51]
	v_mfma_f32_16x16x32_bf16 v[16:19], v[178:181], v[218:221], v[16:19]
	v_mfma_f32_16x16x32_bf16 v[52:55], v[170:173], v[226:229], v[52:55]
	v_mfma_f32_16x16x32_bf16 v[24:27], v[178:181], v[226:229], v[24:27]
	v_mfma_f32_16x16x32_bf16 v[60:63], v[170:173], v[234:237], v[60:63]
	v_mfma_f32_16x16x32_bf16 v[28:31], v[178:181], v[234:237], v[28:31]
	v_mfma_f32_16x16x32_bf16 v[56:59], v[170:173], v[242:245], v[56:59]
	v_mfma_f32_16x16x32_bf16 v[20:23], v[178:181], v[242:245], v[20:23]
	v_mfma_f32_16x16x32_bf16 v[44:47], v[182:185], v[214:217], 0
	v_mfma_f32_16x16x32_bf16 v[12:15], v[202:205], v[214:217], 0
	v_mfma_f32_16x16x32_bf16 v[40:43], v[182:185], v[222:225], 0
	v_mfma_f32_16x16x32_bf16 v[8:11], v[202:205], v[222:225], 0
	v_mfma_f32_16x16x32_bf16 v[36:39], v[182:185], v[230:233], 0
	v_mfma_f32_16x16x32_bf16 v[4:7], v[202:205], v[230:233], 0
	v_mfma_f32_16x16x32_bf16 v[32:35], v[182:185], v[238:241], 0
	v_mfma_f32_16x16x32_bf16 v[0:3], v[202:205], v[238:241], 0
	v_mfma_f32_16x16x32_bf16 v[44:47], v[186:189], v[218:221], v[44:47]
	v_mfma_f32_16x16x32_bf16 v[12:15], v[206:209], v[218:221], v[12:15]
	v_mfma_f32_16x16x32_bf16 v[40:43], v[186:189], v[226:229], v[40:43]
	v_mfma_f32_16x16x32_bf16 v[8:11], v[206:209], v[226:229], v[8:11]
	v_mfma_f32_16x16x32_bf16 v[36:39], v[186:189], v[234:237], v[36:39]
	v_mfma_f32_16x16x32_bf16 v[4:7], v[206:209], v[234:237], v[4:7]
	v_mfma_f32_16x16x32_bf16 v[32:35], v[186:189], v[242:245], v[32:35]
	v_mfma_f32_16x16x32_bf16 v[0:3], v[206:209], v[242:245], v[0:3]
	s_barrier
	s_add_i32 s16, 0, 0x18000
	s_add_i32 s17, 0, 0x1c000
	v_add_u32_e32 v178, s16, v196
	v_add_u32_e32 v201, s17, v196
	ds_read_b128 v[148:151], v178
	ds_read_b128 v[170:173], v178 offset:1024
	ds_read_b128 v[174:177], v178 offset:2048
	ds_read_b128 v[178:181], v178 offset:3072
	ds_read_b128 v[182:185], v201
	ds_read_b128 v[186:189], v201 offset:1024
	ds_read_b128 v[202:205], v201 offset:2048
	ds_read_b128 v[206:209], v201 offset:3072
	s_add_u32 s10, s10, 0x80000
	s_addc_u32 s11, s11, 0
	s_mov_b32 m0, s74
	ds_read_b128 v[214:217], v199 offset:32768
	ds_read_b128 v[218:221], v199 offset:33792
	ds_read_b128 v[222:225], v199 offset:34816
	ds_read_b128 v[226:229], v199 offset:35840
	ds_read_b128 v[230:233], v199 offset:36864
	ds_read_b128 v[234:237], v199 offset:37888
	ds_read_b128 v[238:241], v199 offset:38912
	ds_read_b128 v[242:245], v199 offset:39936
	global_load_lds_dwordx4 v152, s[10:11]
	s_mov_b32 m0, s75
	s_nop 0
	global_load_lds_dwordx4 v156, s[10:11]
	s_waitcnt vmcnt(8)
	s_waitcnt lgkmcnt(0)
	s_barrier
	v_mfma_f32_16x16x32_bf16 v[112:115], v[148:151], v[214:217], v[112:115]
	v_mfma_f32_16x16x32_bf16 v[80:83], v[174:177], v[214:217], v[80:83]
	v_mfma_f32_16x16x32_bf16 v[116:119], v[148:151], v[222:225], v[116:119]
	v_mfma_f32_16x16x32_bf16 v[88:91], v[174:177], v[222:225], v[88:91]
	v_mfma_f32_16x16x32_bf16 v[124:127], v[148:151], v[230:233], v[124:127]
	v_mfma_f32_16x16x32_bf16 v[92:95], v[174:177], v[230:233], v[92:95]
	v_mfma_f32_16x16x32_bf16 v[120:123], v[148:151], v[238:241], v[120:123]
	v_mfma_f32_16x16x32_bf16 v[84:87], v[174:177], v[238:241], v[84:87]
	v_mfma_f32_16x16x32_bf16 v[112:115], v[170:173], v[218:221], v[112:115]
	v_mfma_f32_16x16x32_bf16 v[80:83], v[178:181], v[218:221], v[80:83]
	v_mfma_f32_16x16x32_bf16 v[116:119], v[170:173], v[226:229], v[116:119]
	v_mfma_f32_16x16x32_bf16 v[88:91], v[178:181], v[226:229], v[88:91]
	v_mfma_f32_16x16x32_bf16 v[124:127], v[170:173], v[234:237], v[124:127]
	v_mfma_f32_16x16x32_bf16 v[92:95], v[178:181], v[234:237], v[92:95]
	v_mfma_f32_16x16x32_bf16 v[120:123], v[170:173], v[242:245], v[120:123]
	v_mfma_f32_16x16x32_bf16 v[84:87], v[178:181], v[242:245], v[84:87]
	v_mfma_f32_16x16x32_bf16 v[108:111], v[182:185], v[214:217], v[108:111]
	v_mfma_f32_16x16x32_bf16 v[76:79], v[202:205], v[214:217], v[76:79]
	v_mfma_f32_16x16x32_bf16 v[104:107], v[182:185], v[222:225], v[104:107]
	v_mfma_f32_16x16x32_bf16 v[72:75], v[202:205], v[222:225], v[72:75]
	v_mfma_f32_16x16x32_bf16 v[100:103], v[182:185], v[230:233], v[100:103]
	v_mfma_f32_16x16x32_bf16 v[68:71], v[202:205], v[230:233], v[68:71]
	v_mfma_f32_16x16x32_bf16 v[96:99], v[182:185], v[238:241], v[96:99]
	v_mfma_f32_16x16x32_bf16 v[64:67], v[202:205], v[238:241], v[64:67]
	v_mfma_f32_16x16x32_bf16 v[108:111], v[186:189], v[218:221], v[108:111]
	v_mfma_f32_16x16x32_bf16 v[76:79], v[206:209], v[218:221], v[76:79]
	v_mfma_f32_16x16x32_bf16 v[104:107], v[186:189], v[226:229], v[104:107]
	v_mfma_f32_16x16x32_bf16 v[72:75], v[206:209], v[226:229], v[72:75]
	v_mfma_f32_16x16x32_bf16 v[100:103], v[186:189], v[234:237], v[100:103]
	v_mfma_f32_16x16x32_bf16 v[68:71], v[206:209], v[234:237], v[68:71]
	v_mfma_f32_16x16x32_bf16 v[96:99], v[186:189], v[242:245], v[96:99]
	v_mfma_f32_16x16x32_bf16 v[64:67], v[206:209], v[242:245], v[64:67]
	s_barrier
	s_add_i32 s10, s16, s63
	s_mov_b32 m0, s10
	ds_read_b128 v[214:217], v199 offset:49152
	ds_read_b128 v[218:221], v199 offset:50176
	ds_read_b128 v[222:225], v199 offset:51200
	ds_read_b128 v[226:229], v199 offset:52224
	ds_read_b128 v[230:233], v199 offset:53248
	ds_read_b128 v[234:237], v199 offset:54272
	ds_read_b128 v[238:241], v199 offset:55296
	ds_read_b128 v[242:245], v199 offset:56320
	global_load_lds_dwordx4 v154, s[98:99]
	s_add_i32 m0, s10, 0x2000
	s_add_u32 s8, s8, 0x80080
	s_addc_u32 s9, s9, 0
	s_add_i32 s10, s17, s63
	global_load_lds_dwordx4 v158, s[98:99]
	s_mov_b32 m0, s10
	s_nop 0
	global_load_lds_dwordx4 v154, s[8:9]
	s_add_i32 m0, s10, 0x2000
	s_nop 0
	global_load_lds_dwordx4 v158, s[8:9]
	s_mov_b32 m0, s82
	s_nop 0
	global_load_lds_dwordx4 v152, s[100:101]
	s_mov_b32 m0, s83
	s_nop 0
	global_load_lds_dwordx4 v156, s[100:101]
	s_waitcnt vmcnt(8)
	s_waitcnt lgkmcnt(0)
	s_barrier
	v_mfma_f32_16x16x32_bf16 v[48:51], v[148:151], v[214:217], v[48:51]
	v_mfma_f32_16x16x32_bf16 v[16:19], v[174:177], v[214:217], v[16:19]
	v_mfma_f32_16x16x32_bf16 v[52:55], v[148:151], v[222:225], v[52:55]
	v_mfma_f32_16x16x32_bf16 v[24:27], v[174:177], v[222:225], v[24:27]
	v_mfma_f32_16x16x32_bf16 v[60:63], v[148:151], v[230:233], v[60:63]
	v_mfma_f32_16x16x32_bf16 v[28:31], v[174:177], v[230:233], v[28:31]
	v_mfma_f32_16x16x32_bf16 v[56:59], v[148:151], v[238:241], v[56:59]
	v_mfma_f32_16x16x32_bf16 v[20:23], v[174:177], v[238:241], v[20:23]
	v_mfma_f32_16x16x32_bf16 v[48:51], v[170:173], v[218:221], v[48:51]
	v_mfma_f32_16x16x32_bf16 v[16:19], v[178:181], v[218:221], v[16:19]
	v_mfma_f32_16x16x32_bf16 v[52:55], v[170:173], v[226:229], v[52:55]
	v_mfma_f32_16x16x32_bf16 v[24:27], v[178:181], v[226:229], v[24:27]
	v_mfma_f32_16x16x32_bf16 v[60:63], v[170:173], v[234:237], v[60:63]
	v_mfma_f32_16x16x32_bf16 v[28:31], v[178:181], v[234:237], v[28:31]
	v_mfma_f32_16x16x32_bf16 v[56:59], v[170:173], v[242:245], v[56:59]
	v_mfma_f32_16x16x32_bf16 v[20:23], v[178:181], v[242:245], v[20:23]
	v_mfma_f32_16x16x32_bf16 v[44:47], v[182:185], v[214:217], v[44:47]
	v_mfma_f32_16x16x32_bf16 v[12:15], v[202:205], v[214:217], v[12:15]
	v_mfma_f32_16x16x32_bf16 v[40:43], v[182:185], v[222:225], v[40:43]
	v_mfma_f32_16x16x32_bf16 v[8:11], v[202:205], v[222:225], v[8:11]
	v_mfma_f32_16x16x32_bf16 v[36:39], v[182:185], v[230:233], v[36:39]
	v_mfma_f32_16x16x32_bf16 v[4:7], v[202:205], v[230:233], v[4:7]
	v_mfma_f32_16x16x32_bf16 v[32:35], v[182:185], v[238:241], v[32:35]
	v_mfma_f32_16x16x32_bf16 v[0:3], v[202:205], v[238:241], v[0:3]
	v_mfma_f32_16x16x32_bf16 v[44:47], v[186:189], v[218:221], v[44:47]
	v_mfma_f32_16x16x32_bf16 v[12:15], v[206:209], v[218:221], v[12:15]
	v_mfma_f32_16x16x32_bf16 v[40:43], v[186:189], v[226:229], v[40:43]
	v_mfma_f32_16x16x32_bf16 v[8:11], v[206:209], v[226:229], v[8:11]
	v_mfma_f32_16x16x32_bf16 v[36:39], v[186:189], v[234:237], v[36:39]
	v_mfma_f32_16x16x32_bf16 v[4:7], v[206:209], v[234:237], v[4:7]
	v_mfma_f32_16x16x32_bf16 v[32:35], v[186:189], v[242:245], v[32:35]
	v_mfma_f32_16x16x32_bf16 v[0:3], v[206:209], v[242:245], v[0:3]
	s_barrier
	s_add_i32 s15, s15, 2
	s_add_u32 s6, s6, 0x100
	s_addc_u32 s7, s7, 0
	s_add_u32 s12, s12, 0x100
	s_addc_u32 s13, s13, 0
	s_cmp_gt_u32 s15, 29
.LBB0_636:
	ds_read_b128 v[148:151], v197
	ds_read_b128 v[170:173], v197 offset:1024
	ds_read_b128 v[174:177], v197 offset:2048
	ds_read_b128 v[178:181], v197 offset:3072
	ds_read_b128 v[182:185], v198
	ds_read_b128 v[186:189], v198 offset:1024
	ds_read_b128 v[202:205], v198 offset:2048
	ds_read_b128 v[206:209], v198 offset:3072
	s_add_u32 s8, s6, 0xfff80080
	s_addc_u32 s9, s7, -1
	s_cmp_eq_u32 s15, 28
	s_cselect_b32 s11, s69, s9
	s_cselect_b32 s10, s68, s8
	s_cselect_b32 s9, s1, s13
	s_cselect_b32 s8, s3, s12
	s_add_i32 m0, s72, 0xc000
	ds_read_b128 v[214:217], v199
	ds_read_b128 v[218:221], v199 offset:1024
	ds_read_b128 v[222:225], v199 offset:2048
	ds_read_b128 v[226:229], v199 offset:3072
	ds_read_b128 v[230:233], v199 offset:4096
	ds_read_b128 v[234:237], v199 offset:5120
	ds_read_b128 v[238:241], v199 offset:6144
	ds_read_b128 v[242:245], v199 offset:7168
	global_load_lds_dwordx4 v162, s[6:7]
	s_add_i32 m0, s72, 0xe000
	s_nop 0
	global_load_lds_dwordx4 v164, s[6:7]
	s_waitcnt vmcnt(8)
	s_waitcnt lgkmcnt(0)
	s_barrier
	v_mfma_f32_16x16x32_bf16 v[112:115], v[148:151], v[214:217], v[112:115]
	v_mfma_f32_16x16x32_bf16 v[80:83], v[174:177], v[214:217], v[80:83]
	v_mfma_f32_16x16x32_bf16 v[116:119], v[148:151], v[222:225], v[116:119]
	v_mfma_f32_16x16x32_bf16 v[88:91], v[174:177], v[222:225], v[88:91]
	v_mfma_f32_16x16x32_bf16 v[124:127], v[148:151], v[230:233], v[124:127]
	v_mfma_f32_16x16x32_bf16 v[92:95], v[174:177], v[230:233], v[92:95]
	v_mfma_f32_16x16x32_bf16 v[120:123], v[148:151], v[238:241], v[120:123]
	v_mfma_f32_16x16x32_bf16 v[84:87], v[174:177], v[238:241], v[84:87]
	v_mfma_f32_16x16x32_bf16 v[112:115], v[170:173], v[218:221], v[112:115]
	v_mfma_f32_16x16x32_bf16 v[80:83], v[178:181], v[218:221], v[80:83]
	v_mfma_f32_16x16x32_bf16 v[116:119], v[170:173], v[226:229], v[116:119]
	v_mfma_f32_16x16x32_bf16 v[88:91], v[178:181], v[226:229], v[88:91]
	v_mfma_f32_16x16x32_bf16 v[124:127], v[170:173], v[234:237], v[124:127]
	v_mfma_f32_16x16x32_bf16 v[92:95], v[178:181], v[234:237], v[92:95]
	v_mfma_f32_16x16x32_bf16 v[120:123], v[170:173], v[242:245], v[120:123]
	v_mfma_f32_16x16x32_bf16 v[84:87], v[178:181], v[242:245], v[84:87]
	v_mfma_f32_16x16x32_bf16 v[108:111], v[182:185], v[214:217], v[108:111]
	v_mfma_f32_16x16x32_bf16 v[76:79], v[202:205], v[214:217], v[76:79]
	v_mfma_f32_16x16x32_bf16 v[104:107], v[182:185], v[222:225], v[104:107]
	v_mfma_f32_16x16x32_bf16 v[72:75], v[202:205], v[222:225], v[72:75]
	v_mfma_f32_16x16x32_bf16 v[100:103], v[182:185], v[230:233], v[100:103]
	v_mfma_f32_16x16x32_bf16 v[68:71], v[202:205], v[230:233], v[68:71]
	v_mfma_f32_16x16x32_bf16 v[96:99], v[182:185], v[238:241], v[96:99]
	v_mfma_f32_16x16x32_bf16 v[64:67], v[202:205], v[238:241], v[64:67]
	v_mfma_f32_16x16x32_bf16 v[108:111], v[186:189], v[218:221], v[108:111]
	v_mfma_f32_16x16x32_bf16 v[76:79], v[206:209], v[218:221], v[76:79]
	v_mfma_f32_16x16x32_bf16 v[104:107], v[186:189], v[226:229], v[104:107]
	v_mfma_f32_16x16x32_bf16 v[72:75], v[206:209], v[226:229], v[72:75]
	v_mfma_f32_16x16x32_bf16 v[100:103], v[186:189], v[234:237], v[100:103]
	v_mfma_f32_16x16x32_bf16 v[68:71], v[206:209], v[234:237], v[68:71]
	v_mfma_f32_16x16x32_bf16 v[96:99], v[186:189], v[242:245], v[96:99]
	v_mfma_f32_16x16x32_bf16 v[64:67], v[206:209], v[242:245], v[64:67]
	s_barrier
	s_add_i32 s16, s94, s63
	s_add_u32 s98, s8, s40
	s_addc_u32 s99, s9, s41
	s_mov_b32 m0, s16
	ds_read_b128 v[214:217], v199 offset:16384
	ds_read_b128 v[218:221], v199 offset:17408
	ds_read_b128 v[222:225], v199 offset:18432
	ds_read_b128 v[226:229], v199 offset:19456
	ds_read_b128 v[230:233], v199 offset:20480
	ds_read_b128 v[234:237], v199 offset:21504
	ds_read_b128 v[238:241], v199 offset:22528
	ds_read_b128 v[242:245], v199 offset:23552
	global_load_lds_dwordx4 v154, s[8:9]
	s_add_i32 m0, s16, 0x2000
	s_add_u32 s16, s8, 0x80000
	s_addc_u32 s17, s9, 0
	s_add_i32 s18, s95, s63
	global_load_lds_dwordx4 v158, s[8:9]
	s_mov_b32 m0, s18
	s_add_u32 s100, s10, s40
	s_addc_u32 s101, s11, s41
	global_load_lds_dwordx4 v154, s[16:17]
	s_add_i32 m0, s18, 0x2000
	s_nop 0
	global_load_lds_dwordx4 v158, s[16:17]
	s_mov_b32 m0, s72
	s_nop 0
	global_load_lds_dwordx4 v152, s[10:11]
	s_mov_b32 m0, s73
	s_nop 0
	global_load_lds_dwordx4 v156, s[10:11]
	s_waitcnt vmcnt(8)
	s_waitcnt lgkmcnt(0)
	s_barrier
	v_mfma_f32_16x16x32_bf16 v[48:51], v[148:151], v[214:217], v[48:51]
	v_mfma_f32_16x16x32_bf16 v[16:19], v[174:177], v[214:217], v[16:19]
	v_mfma_f32_16x16x32_bf16 v[52:55], v[148:151], v[222:225], v[52:55]
	v_mfma_f32_16x16x32_bf16 v[24:27], v[174:177], v[222:225], v[24:27]
	v_mfma_f32_16x16x32_bf16 v[60:63], v[148:151], v[230:233], v[60:63]
	v_mfma_f32_16x16x32_bf16 v[28:31], v[174:177], v[230:233], v[28:31]
	v_mfma_f32_16x16x32_bf16 v[56:59], v[148:151], v[238:241], v[56:59]
	v_mfma_f32_16x16x32_bf16 v[20:23], v[174:177], v[238:241], v[20:23]
	v_mfma_f32_16x16x32_bf16 v[48:51], v[170:173], v[218:221], v[48:51]
	v_mfma_f32_16x16x32_bf16 v[16:19], v[178:181], v[218:221], v[16:19]
	v_mfma_f32_16x16x32_bf16 v[52:55], v[170:173], v[226:229], v[52:55]
	v_mfma_f32_16x16x32_bf16 v[24:27], v[178:181], v[226:229], v[24:27]
	v_mfma_f32_16x16x32_bf16 v[60:63], v[170:173], v[234:237], v[60:63]
	v_mfma_f32_16x16x32_bf16 v[28:31], v[178:181], v[234:237], v[28:31]
	v_mfma_f32_16x16x32_bf16 v[56:59], v[170:173], v[242:245], v[56:59]
	v_mfma_f32_16x16x32_bf16 v[20:23], v[178:181], v[242:245], v[20:23]
	v_mfma_f32_16x16x32_bf16 v[44:47], v[182:185], v[214:217], v[44:47]
	v_mfma_f32_16x16x32_bf16 v[12:15], v[202:205], v[214:217], v[12:15]
	v_mfma_f32_16x16x32_bf16 v[40:43], v[182:185], v[222:225], v[40:43]
	v_mfma_f32_16x16x32_bf16 v[8:11], v[202:205], v[222:225], v[8:11]
	v_mfma_f32_16x16x32_bf16 v[36:39], v[182:185], v[230:233], v[36:39]
	v_mfma_f32_16x16x32_bf16 v[4:7], v[202:205], v[230:233], v[4:7]
	v_mfma_f32_16x16x32_bf16 v[32:35], v[182:185], v[238:241], v[32:35]
	v_mfma_f32_16x16x32_bf16 v[0:3], v[202:205], v[238:241], v[0:3]
	v_mfma_f32_16x16x32_bf16 v[44:47], v[186:189], v[218:221], v[44:47]
	v_mfma_f32_16x16x32_bf16 v[12:15], v[206:209], v[218:221], v[12:15]
	v_mfma_f32_16x16x32_bf16 v[40:43], v[186:189], v[226:229], v[40:43]
	v_mfma_f32_16x16x32_bf16 v[8:11], v[206:209], v[226:229], v[8:11]
	v_mfma_f32_16x16x32_bf16 v[36:39], v[186:189], v[234:237], v[36:39]
	v_mfma_f32_16x16x32_bf16 v[4:7], v[206:209], v[234:237], v[4:7]
	v_mfma_f32_16x16x32_bf16 v[32:35], v[186:189], v[242:245], v[32:35]
	v_mfma_f32_16x16x32_bf16 v[0:3], v[206:209], v[242:245], v[0:3]
	s_barrier
	s_add_i32 s16, 0, 0x18000
	s_add_i32 s17, 0, 0x1c000
	v_add_u32_e32 v178, s16, v196
	v_add_u32_e32 v201, s17, v196
	ds_read_b128 v[148:151], v178
	ds_read_b128 v[170:173], v178 offset:1024
	ds_read_b128 v[174:177], v178 offset:2048
	ds_read_b128 v[178:181], v178 offset:3072
	ds_read_b128 v[182:185], v201
	ds_read_b128 v[186:189], v201 offset:1024
	ds_read_b128 v[202:205], v201 offset:2048
	ds_read_b128 v[206:209], v201 offset:3072
	s_add_u32 s10, s10, 0x80000
	s_addc_u32 s11, s11, 0
	s_mov_b32 m0, s74
	ds_read_b128 v[214:217], v199 offset:32768
	ds_read_b128 v[218:221], v199 offset:33792
	ds_read_b128 v[222:225], v199 offset:34816
	ds_read_b128 v[226:229], v199 offset:35840
	ds_read_b128 v[230:233], v199 offset:36864
	ds_read_b128 v[234:237], v199 offset:37888
	ds_read_b128 v[238:241], v199 offset:38912
	ds_read_b128 v[242:245], v199 offset:39936
	global_load_lds_dwordx4 v152, s[10:11]
	s_mov_b32 m0, s75
	s_nop 0
	global_load_lds_dwordx4 v156, s[10:11]
	s_waitcnt vmcnt(8)
	s_waitcnt lgkmcnt(0)
	s_barrier
	v_mfma_f32_16x16x32_bf16 v[112:115], v[148:151], v[214:217], v[112:115]
	v_mfma_f32_16x16x32_bf16 v[80:83], v[174:177], v[214:217], v[80:83]
	v_mfma_f32_16x16x32_bf16 v[116:119], v[148:151], v[222:225], v[116:119]
	v_mfma_f32_16x16x32_bf16 v[88:91], v[174:177], v[222:225], v[88:91]
	v_mfma_f32_16x16x32_bf16 v[124:127], v[148:151], v[230:233], v[124:127]
	v_mfma_f32_16x16x32_bf16 v[92:95], v[174:177], v[230:233], v[92:95]
	v_mfma_f32_16x16x32_bf16 v[120:123], v[148:151], v[238:241], v[120:123]
	v_mfma_f32_16x16x32_bf16 v[84:87], v[174:177], v[238:241], v[84:87]
	v_mfma_f32_16x16x32_bf16 v[112:115], v[170:173], v[218:221], v[112:115]
	v_mfma_f32_16x16x32_bf16 v[80:83], v[178:181], v[218:221], v[80:83]
	v_mfma_f32_16x16x32_bf16 v[116:119], v[170:173], v[226:229], v[116:119]
	v_mfma_f32_16x16x32_bf16 v[88:91], v[178:181], v[226:229], v[88:91]
	v_mfma_f32_16x16x32_bf16 v[124:127], v[170:173], v[234:237], v[124:127]
	v_mfma_f32_16x16x32_bf16 v[92:95], v[178:181], v[234:237], v[92:95]
	v_mfma_f32_16x16x32_bf16 v[120:123], v[170:173], v[242:245], v[120:123]
	v_mfma_f32_16x16x32_bf16 v[84:87], v[178:181], v[242:245], v[84:87]
	v_mfma_f32_16x16x32_bf16 v[108:111], v[182:185], v[214:217], v[108:111]
	v_mfma_f32_16x16x32_bf16 v[76:79], v[202:205], v[214:217], v[76:79]
	v_mfma_f32_16x16x32_bf16 v[104:107], v[182:185], v[222:225], v[104:107]
	v_mfma_f32_16x16x32_bf16 v[72:75], v[202:205], v[222:225], v[72:75]
	v_mfma_f32_16x16x32_bf16 v[100:103], v[182:185], v[230:233], v[100:103]
	v_mfma_f32_16x16x32_bf16 v[68:71], v[202:205], v[230:233], v[68:71]
	v_mfma_f32_16x16x32_bf16 v[96:99], v[182:185], v[238:241], v[96:99]
	v_mfma_f32_16x16x32_bf16 v[64:67], v[202:205], v[238:241], v[64:67]
	v_mfma_f32_16x16x32_bf16 v[108:111], v[186:189], v[218:221], v[108:111]
	v_mfma_f32_16x16x32_bf16 v[76:79], v[206:209], v[218:221], v[76:79]
	v_mfma_f32_16x16x32_bf16 v[104:107], v[186:189], v[226:229], v[104:107]
	v_mfma_f32_16x16x32_bf16 v[72:75], v[206:209], v[226:229], v[72:75]
	v_mfma_f32_16x16x32_bf16 v[100:103], v[186:189], v[234:237], v[100:103]
	v_mfma_f32_16x16x32_bf16 v[68:71], v[206:209], v[234:237], v[68:71]
	v_mfma_f32_16x16x32_bf16 v[96:99], v[186:189], v[242:245], v[96:99]
	v_mfma_f32_16x16x32_bf16 v[64:67], v[206:209], v[242:245], v[64:67]
	s_barrier
	s_add_i32 s10, s16, s63
	s_mov_b32 m0, s10
	ds_read_b128 v[214:217], v199 offset:49152
	ds_read_b128 v[218:221], v199 offset:50176
	ds_read_b128 v[222:225], v199 offset:51200
	ds_read_b128 v[226:229], v199 offset:52224
	ds_read_b128 v[230:233], v199 offset:53248
	ds_read_b128 v[234:237], v199 offset:54272
	ds_read_b128 v[238:241], v199 offset:55296
	ds_read_b128 v[242:245], v199 offset:56320
	global_load_lds_dwordx4 v154, s[98:99]
	s_add_i32 m0, s10, 0x2000
	s_add_u32 s8, s8, 0x80080
	s_addc_u32 s9, s9, 0
	s_add_i32 s10, s17, s63
	global_load_lds_dwordx4 v158, s[98:99]
	s_mov_b32 m0, s10
	s_nop 0
	global_load_lds_dwordx4 v154, s[8:9]
	s_add_i32 m0, s10, 0x2000
	s_nop 0
	global_load_lds_dwordx4 v158, s[8:9]
	s_mov_b32 m0, s82
	s_nop 0
	global_load_lds_dwordx4 v152, s[100:101]
	s_mov_b32 m0, s83
	s_nop 0
	global_load_lds_dwordx4 v156, s[100:101]
	s_waitcnt vmcnt(8)
	s_waitcnt lgkmcnt(0)
	s_barrier
	v_mfma_f32_16x16x32_bf16 v[48:51], v[148:151], v[214:217], v[48:51]
	v_mfma_f32_16x16x32_bf16 v[16:19], v[174:177], v[214:217], v[16:19]
	v_mfma_f32_16x16x32_bf16 v[52:55], v[148:151], v[222:225], v[52:55]
	v_mfma_f32_16x16x32_bf16 v[24:27], v[174:177], v[222:225], v[24:27]
	v_mfma_f32_16x16x32_bf16 v[60:63], v[148:151], v[230:233], v[60:63]
	v_mfma_f32_16x16x32_bf16 v[28:31], v[174:177], v[230:233], v[28:31]
	v_mfma_f32_16x16x32_bf16 v[56:59], v[148:151], v[238:241], v[56:59]
	v_mfma_f32_16x16x32_bf16 v[20:23], v[174:177], v[238:241], v[20:23]
	v_mfma_f32_16x16x32_bf16 v[48:51], v[170:173], v[218:221], v[48:51]
	v_mfma_f32_16x16x32_bf16 v[16:19], v[178:181], v[218:221], v[16:19]
	v_mfma_f32_16x16x32_bf16 v[52:55], v[170:173], v[226:229], v[52:55]
	v_mfma_f32_16x16x32_bf16 v[24:27], v[178:181], v[226:229], v[24:27]
	v_mfma_f32_16x16x32_bf16 v[60:63], v[170:173], v[234:237], v[60:63]
	v_mfma_f32_16x16x32_bf16 v[28:31], v[178:181], v[234:237], v[28:31]
	v_mfma_f32_16x16x32_bf16 v[56:59], v[170:173], v[242:245], v[56:59]
	v_mfma_f32_16x16x32_bf16 v[20:23], v[178:181], v[242:245], v[20:23]
	v_mfma_f32_16x16x32_bf16 v[44:47], v[182:185], v[214:217], v[44:47]
	v_mfma_f32_16x16x32_bf16 v[12:15], v[202:205], v[214:217], v[12:15]
	v_mfma_f32_16x16x32_bf16 v[40:43], v[182:185], v[222:225], v[40:43]
	v_mfma_f32_16x16x32_bf16 v[8:11], v[202:205], v[222:225], v[8:11]
	v_mfma_f32_16x16x32_bf16 v[36:39], v[182:185], v[230:233], v[36:39]
	v_mfma_f32_16x16x32_bf16 v[4:7], v[202:205], v[230:233], v[4:7]
	v_mfma_f32_16x16x32_bf16 v[32:35], v[182:185], v[238:241], v[32:35]
	v_mfma_f32_16x16x32_bf16 v[0:3], v[202:205], v[238:241], v[0:3]
	v_mfma_f32_16x16x32_bf16 v[44:47], v[186:189], v[218:221], v[44:47]
	v_mfma_f32_16x16x32_bf16 v[12:15], v[206:209], v[218:221], v[12:15]
	v_mfma_f32_16x16x32_bf16 v[40:43], v[186:189], v[226:229], v[40:43]
	v_mfma_f32_16x16x32_bf16 v[8:11], v[206:209], v[226:229], v[8:11]
	v_mfma_f32_16x16x32_bf16 v[36:39], v[186:189], v[234:237], v[36:39]
	v_mfma_f32_16x16x32_bf16 v[4:7], v[206:209], v[234:237], v[4:7]
	v_mfma_f32_16x16x32_bf16 v[32:35], v[186:189], v[242:245], v[32:35]
	v_mfma_f32_16x16x32_bf16 v[0:3], v[206:209], v[242:245], v[0:3]
	s_barrier
	s_add_i32 s15, s15, 2
	s_add_u32 s6, s6, 0x100
	s_addc_u32 s7, s7, 0
	s_add_u32 s12, s12, 0x100
	s_addc_u32 s13, s13, 0
	s_cmp_gt_u32 s15, 29
	s_cbranch_scc0 .LBB0_636
	s_and_b64 vcc, exec, s[42:43]
	s_cbranch_vccz .LBB0_639
	s_barrier

.LBB0_875:
	s_mov_b32 s1, -2
	s_mov_b64 s[4:5], s[22:23]
	ds_read_b128 v[128:131], v188
	ds_read_b128 v[132:135], v188 offset:1024
	ds_read_b128 v[136:139], v188 offset:2048
	ds_read_b128 v[140:143], v188 offset:3072
	ds_read_b128 v[144:147], v189
	ds_read_b128 v[148:151], v189 offset:1024
	ds_read_b128 v[166:169], v189 offset:2048
	ds_read_b128 v[170:173], v189 offset:3072
	s_add_u32 s40, s38, 0x100
	s_addc_u32 s41, s39, 0
	s_cmpk_eq_i32 s1, 0x52
	s_cselect_b32 s45, s37, s41
	s_cselect_b32 s44, s36, s40
	s_cselect_b32 s43, s17, s5
	s_cselect_b32 s42, s16, s4
	s_add_i32 m0, s48, 0xc000
	ds_read_b128 v[174:177], v190
	ds_read_b128 v[178:181], v190 offset:1024
	ds_read_b128 v[194:197], v190 offset:2048
	ds_read_b128 v[198:201], v190 offset:3072
	ds_read_b128 v[202:205], v190 offset:4096
	ds_read_b128 v[206:209], v190 offset:5120
	ds_read_b128 v[210:213], v190 offset:6144
	ds_read_b128 v[214:217], v190 offset:7168
	global_load_lds_dwordx4 v160, s[38:39]
	s_add_i32 m0, s48, 0xe000
	s_nop 0
	global_load_lds_dwordx4 v162, s[38:39]
	s_waitcnt vmcnt(8)
	s_waitcnt lgkmcnt(0)
	s_barrier
	v_mfma_f32_16x16x32_bf16 v[124:127], v[128:131], v[174:177], 0
	v_mfma_f32_16x16x32_bf16 v[120:123], v[136:139], v[174:177], 0
	v_mfma_f32_16x16x32_bf16 v[108:111], v[128:131], v[194:197], 0
	v_mfma_f32_16x16x32_bf16 v[104:107], v[136:139], v[194:197], 0
	v_mfma_f32_16x16x32_bf16 v[92:95], v[128:131], v[202:205], 0
	v_mfma_f32_16x16x32_bf16 v[88:91], v[136:139], v[202:205], 0
	v_mfma_f32_16x16x32_bf16 v[76:79], v[128:131], v[210:213], 0
	v_mfma_f32_16x16x32_bf16 v[72:75], v[136:139], v[210:213], 0
	v_mfma_f32_16x16x32_bf16 v[124:127], v[132:135], v[178:181], v[124:127]
	v_mfma_f32_16x16x32_bf16 v[120:123], v[140:143], v[178:181], v[120:123]
	v_mfma_f32_16x16x32_bf16 v[108:111], v[132:135], v[198:201], v[108:111]
	v_mfma_f32_16x16x32_bf16 v[104:107], v[140:143], v[198:201], v[104:107]
	v_mfma_f32_16x16x32_bf16 v[92:95], v[132:135], v[206:209], v[92:95]
	v_mfma_f32_16x16x32_bf16 v[88:91], v[140:143], v[206:209], v[88:91]
	v_mfma_f32_16x16x32_bf16 v[76:79], v[132:135], v[214:217], v[76:79]
	v_mfma_f32_16x16x32_bf16 v[72:75], v[140:143], v[214:217], v[72:75]
	v_mfma_f32_16x16x32_bf16 v[116:119], v[144:147], v[174:177], 0
	v_mfma_f32_16x16x32_bf16 v[112:115], v[166:169], v[174:177], 0
	v_mfma_f32_16x16x32_bf16 v[100:103], v[144:147], v[194:197], 0
	v_mfma_f32_16x16x32_bf16 v[96:99], v[166:169], v[194:197], 0
	v_mfma_f32_16x16x32_bf16 v[84:87], v[144:147], v[202:205], 0
	v_mfma_f32_16x16x32_bf16 v[80:83], v[166:169], v[202:205], 0
	v_mfma_f32_16x16x32_bf16 v[68:71], v[144:147], v[210:213], 0
	v_mfma_f32_16x16x32_bf16 v[64:67], v[166:169], v[210:213], 0
	v_mfma_f32_16x16x32_bf16 v[116:119], v[148:151], v[178:181], v[116:119]
	v_mfma_f32_16x16x32_bf16 v[112:115], v[170:173], v[178:181], v[112:115]
	v_mfma_f32_16x16x32_bf16 v[100:103], v[148:151], v[198:201], v[100:103]
	v_mfma_f32_16x16x32_bf16 v[96:99], v[170:173], v[198:201], v[96:99]
	v_mfma_f32_16x16x32_bf16 v[84:87], v[148:151], v[206:209], v[84:87]
	v_mfma_f32_16x16x32_bf16 v[80:83], v[170:173], v[206:209], v[80:83]
	v_mfma_f32_16x16x32_bf16 v[68:71], v[148:151], v[214:217], v[68:71]
	v_mfma_f32_16x16x32_bf16 v[64:67], v[170:173], v[214:217], v[64:67]
	s_barrier
	s_add_i32 s3, s70, s33
	s_add_u32 s98, s42, s24
	s_addc_u32 s99, s43, s25
	s_mov_b32 m0, s3
	ds_read_b128 v[174:177], v190 offset:16384
	ds_read_b128 v[178:181], v190 offset:17408
	ds_read_b128 v[194:197], v190 offset:18432
	ds_read_b128 v[198:201], v190 offset:19456
	ds_read_b128 v[202:205], v190 offset:20480
	ds_read_b128 v[206:209], v190 offset:21504
	ds_read_b128 v[210:213], v190 offset:22528
	ds_read_b128 v[214:217], v190 offset:23552
	global_load_lds_dwordx4 v154, s[42:43]
	s_add_i32 m0, s3, 0x2000
	s_add_u32 s38, s42, 0x158000
	s_addc_u32 s39, s43, 0
	s_add_i32 s3, s71, s33
	global_load_lds_dwordx4 v158, s[42:43]
	s_mov_b32 m0, s3
	s_add_u32 s100, s44, s24
	s_addc_u32 s101, s45, s25
	global_load_lds_dwordx4 v154, s[38:39]
	s_add_i32 m0, s3, 0x2000
	s_nop 0
	global_load_lds_dwordx4 v158, s[38:39]
	s_mov_b32 m0, s48
	s_nop 0
	global_load_lds_dwordx4 v152, s[44:45]
	s_mov_b32 m0, s49
	s_nop 0
	global_load_lds_dwordx4 v156, s[44:45]
	s_waitcnt vmcnt(8)
	s_waitcnt lgkmcnt(0)
	s_barrier
	v_mfma_f32_16x16x32_bf16 v[60:63], v[128:131], v[174:177], 0
	v_mfma_f32_16x16x32_bf16 v[56:59], v[136:139], v[174:177], 0
	v_mfma_f32_16x16x32_bf16 v[44:47], v[128:131], v[194:197], 0
	v_mfma_f32_16x16x32_bf16 v[40:43], v[136:139], v[194:197], 0
	v_mfma_f32_16x16x32_bf16 v[28:31], v[128:131], v[202:205], 0
	v_mfma_f32_16x16x32_bf16 v[24:27], v[136:139], v[202:205], 0
	v_mfma_f32_16x16x32_bf16 v[12:15], v[128:131], v[210:213], 0
	v_mfma_f32_16x16x32_bf16 v[8:11], v[136:139], v[210:213], 0
	v_mfma_f32_16x16x32_bf16 v[60:63], v[132:135], v[178:181], v[60:63]
	v_mfma_f32_16x16x32_bf16 v[56:59], v[140:143], v[178:181], v[56:59]
	v_mfma_f32_16x16x32_bf16 v[44:47], v[132:135], v[198:201], v[44:47]
	v_mfma_f32_16x16x32_bf16 v[40:43], v[140:143], v[198:201], v[40:43]
	v_mfma_f32_16x16x32_bf16 v[28:31], v[132:135], v[206:209], v[28:31]
	v_mfma_f32_16x16x32_bf16 v[24:27], v[140:143], v[206:209], v[24:27]
	v_mfma_f32_16x16x32_bf16 v[12:15], v[132:135], v[214:217], v[12:15]
	v_mfma_f32_16x16x32_bf16 v[8:11], v[140:143], v[214:217], v[8:11]
	v_mfma_f32_16x16x32_bf16 v[52:55], v[144:147], v[174:177], 0
	v_mfma_f32_16x16x32_bf16 v[48:51], v[166:169], v[174:177], 0
	v_mfma_f32_16x16x32_bf16 v[36:39], v[144:147], v[194:197], 0
	v_mfma_f32_16x16x32_bf16 v[32:35], v[166:169], v[194:197], 0
	v_mfma_f32_16x16x32_bf16 v[20:23], v[144:147], v[202:205], 0
	v_mfma_f32_16x16x32_bf16 v[16:19], v[166:169], v[202:205], 0
	v_mfma_f32_16x16x32_bf16 v[4:7], v[144:147], v[210:213], 0
	v_mfma_f32_16x16x32_bf16 v[0:3], v[166:169], v[210:213], 0
	v_mfma_f32_16x16x32_bf16 v[52:55], v[148:151], v[178:181], v[52:55]
	v_mfma_f32_16x16x32_bf16 v[48:51], v[170:173], v[178:181], v[48:51]
	v_mfma_f32_16x16x32_bf16 v[36:39], v[148:151], v[198:201], v[36:39]
	v_mfma_f32_16x16x32_bf16 v[32:35], v[170:173], v[198:201], v[32:35]
	v_mfma_f32_16x16x32_bf16 v[20:23], v[148:151], v[206:209], v[20:23]
	v_mfma_f32_16x16x32_bf16 v[16:19], v[170:173], v[206:209], v[16:19]
	v_mfma_f32_16x16x32_bf16 v[4:7], v[148:151], v[214:217], v[4:7]
	v_mfma_f32_16x16x32_bf16 v[0:3], v[170:173], v[214:217], v[0:3]
	s_barrier
	s_add_i32 s3, 0, 0x18000
	s_add_i32 s73, 0, 0x1c000
	v_add_u32_e32 v140, s3, v187
	v_add_u32_e32 v170, s73, v187
	ds_read_b128 v[128:131], v140
	ds_read_b128 v[132:135], v140 offset:1024
	ds_read_b128 v[136:139], v140 offset:2048
	ds_read_b128 v[140:143], v140 offset:3072
	ds_read_b128 v[144:147], v170
	ds_read_b128 v[148:151], v170 offset:1024
	ds_read_b128 v[166:169], v170 offset:2048
	ds_read_b128 v[170:173], v170 offset:3072
	s_add_u32 s38, s44, 0x158000
	s_addc_u32 s39, s45, 0
	s_mov_b32 m0, s51
	ds_read_b128 v[174:177], v190 offset:32768
	ds_read_b128 v[178:181], v190 offset:33792
	ds_read_b128 v[194:197], v190 offset:34816
	ds_read_b128 v[198:201], v190 offset:35840
	ds_read_b128 v[202:205], v190 offset:36864
	ds_read_b128 v[206:209], v190 offset:37888
	ds_read_b128 v[210:213], v190 offset:38912
	ds_read_b128 v[214:217], v190 offset:39936
	global_load_lds_dwordx4 v152, s[38:39]
	s_mov_b32 m0, s52
	s_nop 0
	global_load_lds_dwordx4 v156, s[38:39]
	s_waitcnt vmcnt(8)
	s_waitcnt lgkmcnt(0)
	s_barrier
	v_mfma_f32_16x16x32_bf16 v[124:127], v[128:131], v[174:177], v[124:127]
	v_mfma_f32_16x16x32_bf16 v[120:123], v[136:139], v[174:177], v[120:123]
	v_mfma_f32_16x16x32_bf16 v[108:111], v[128:131], v[194:197], v[108:111]
	v_mfma_f32_16x16x32_bf16 v[104:107], v[136:139], v[194:197], v[104:107]
	v_mfma_f32_16x16x32_bf16 v[92:95], v[128:131], v[202:205], v[92:95]
	v_mfma_f32_16x16x32_bf16 v[88:91], v[136:139], v[202:205], v[88:91]
	v_mfma_f32_16x16x32_bf16 v[76:79], v[128:131], v[210:213], v[76:79]
	v_mfma_f32_16x16x32_bf16 v[72:75], v[136:139], v[210:213], v[72:75]
	v_mfma_f32_16x16x32_bf16 v[124:127], v[132:135], v[178:181], v[124:127]
	v_mfma_f32_16x16x32_bf16 v[120:123], v[140:143], v[178:181], v[120:123]
	v_mfma_f32_16x16x32_bf16 v[108:111], v[132:135], v[198:201], v[108:111]
	v_mfma_f32_16x16x32_bf16 v[104:107], v[140:143], v[198:201], v[104:107]
	v_mfma_f32_16x16x32_bf16 v[92:95], v[132:135], v[206:209], v[92:95]
	v_mfma_f32_16x16x32_bf16 v[88:91], v[140:143], v[206:209], v[88:91]
	v_mfma_f32_16x16x32_bf16 v[76:79], v[132:135], v[214:217], v[76:79]
	v_mfma_f32_16x16x32_bf16 v[72:75], v[140:143], v[214:217], v[72:75]
	v_mfma_f32_16x16x32_bf16 v[116:119], v[144:147], v[174:177], v[116:119]
	v_mfma_f32_16x16x32_bf16 v[112:115], v[166:169], v[174:177], v[112:115]
	v_mfma_f32_16x16x32_bf16 v[100:103], v[144:147], v[194:197], v[100:103]
	v_mfma_f32_16x16x32_bf16 v[96:99], v[166:169], v[194:197], v[96:99]
	v_mfma_f32_16x16x32_bf16 v[84:87], v[144:147], v[202:205], v[84:87]
	v_mfma_f32_16x16x32_bf16 v[80:83], v[166:169], v[202:205], v[80:83]
	v_mfma_f32_16x16x32_bf16 v[68:71], v[144:147], v[210:213], v[68:71]
	v_mfma_f32_16x16x32_bf16 v[64:67], v[166:169], v[210:213], v[64:67]
	v_mfma_f32_16x16x32_bf16 v[116:119], v[148:151], v[178:181], v[116:119]
	v_mfma_f32_16x16x32_bf16 v[112:115], v[170:173], v[178:181], v[112:115]
	v_mfma_f32_16x16x32_bf16 v[100:103], v[148:151], v[198:201], v[100:103]
	v_mfma_f32_16x16x32_bf16 v[96:99], v[170:173], v[198:201], v[96:99]
	v_mfma_f32_16x16x32_bf16 v[84:87], v[148:151], v[206:209], v[84:87]
	v_mfma_f32_16x16x32_bf16 v[80:83], v[170:173], v[206:209], v[80:83]
	v_mfma_f32_16x16x32_bf16 v[68:71], v[148:151], v[214:217], v[68:71]
	v_mfma_f32_16x16x32_bf16 v[64:67], v[170:173], v[214:217], v[64:67]
	s_barrier
	s_add_i32 s3, s3, s33
	s_mov_b32 m0, s3
	ds_read_b128 v[174:177], v190 offset:49152
	ds_read_b128 v[178:181], v190 offset:50176
	ds_read_b128 v[194:197], v190 offset:51200
	ds_read_b128 v[198:201], v190 offset:52224
	ds_read_b128 v[202:205], v190 offset:53248
	ds_read_b128 v[206:209], v190 offset:54272
	ds_read_b128 v[210:213], v190 offset:55296
	ds_read_b128 v[214:217], v190 offset:56320
	global_load_lds_dwordx4 v154, s[98:99]
	s_add_i32 m0, s3, 0x2000
	s_add_u32 s38, s42, 0x158080
	s_addc_u32 s39, s43, 0
	s_add_i32 s3, s73, s33
	global_load_lds_dwordx4 v158, s[98:99]
	s_mov_b32 m0, s3
	s_nop 0
	global_load_lds_dwordx4 v154, s[38:39]
	s_add_i32 m0, s3, 0x2000
	s_nop 0
	global_load_lds_dwordx4 v158, s[38:39]
	s_mov_b32 m0, s56
	s_nop 0
	global_load_lds_dwordx4 v152, s[100:101]
	s_mov_b32 m0, s57
	s_nop 0
	global_load_lds_dwordx4 v156, s[100:101]
	s_waitcnt vmcnt(8)
	s_waitcnt lgkmcnt(0)
	s_barrier
	v_mfma_f32_16x16x32_bf16 v[60:63], v[128:131], v[174:177], v[60:63]
	v_mfma_f32_16x16x32_bf16 v[56:59], v[136:139], v[174:177], v[56:59]
	v_mfma_f32_16x16x32_bf16 v[44:47], v[128:131], v[194:197], v[44:47]
	v_mfma_f32_16x16x32_bf16 v[40:43], v[136:139], v[194:197], v[40:43]
	v_mfma_f32_16x16x32_bf16 v[28:31], v[128:131], v[202:205], v[28:31]
	v_mfma_f32_16x16x32_bf16 v[24:27], v[136:139], v[202:205], v[24:27]
	v_mfma_f32_16x16x32_bf16 v[12:15], v[128:131], v[210:213], v[12:15]
	v_mfma_f32_16x16x32_bf16 v[8:11], v[136:139], v[210:213], v[8:11]
	v_mfma_f32_16x16x32_bf16 v[60:63], v[132:135], v[178:181], v[60:63]
	v_mfma_f32_16x16x32_bf16 v[56:59], v[140:143], v[178:181], v[56:59]
	v_mfma_f32_16x16x32_bf16 v[44:47], v[132:135], v[198:201], v[44:47]
	v_mfma_f32_16x16x32_bf16 v[40:43], v[140:143], v[198:201], v[40:43]
	v_mfma_f32_16x16x32_bf16 v[28:31], v[132:135], v[206:209], v[28:31]
	v_mfma_f32_16x16x32_bf16 v[24:27], v[140:143], v[206:209], v[24:27]
	v_mfma_f32_16x16x32_bf16 v[12:15], v[132:135], v[214:217], v[12:15]
	v_mfma_f32_16x16x32_bf16 v[8:11], v[140:143], v[214:217], v[8:11]
	v_mfma_f32_16x16x32_bf16 v[52:55], v[144:147], v[174:177], v[52:55]
	v_mfma_f32_16x16x32_bf16 v[48:51], v[166:169], v[174:177], v[48:51]
	v_mfma_f32_16x16x32_bf16 v[36:39], v[144:147], v[194:197], v[36:39]
	v_mfma_f32_16x16x32_bf16 v[32:35], v[166:169], v[194:197], v[32:35]
	v_mfma_f32_16x16x32_bf16 v[20:23], v[144:147], v[202:205], v[20:23]
	v_mfma_f32_16x16x32_bf16 v[16:19], v[166:169], v[202:205], v[16:19]
	v_mfma_f32_16x16x32_bf16 v[4:7], v[144:147], v[210:213], v[4:7]
	v_mfma_f32_16x16x32_bf16 v[0:3], v[166:169], v[210:213], v[0:3]
	v_mfma_f32_16x16x32_bf16 v[52:55], v[148:151], v[178:181], v[52:55]
	v_mfma_f32_16x16x32_bf16 v[48:51], v[170:173], v[178:181], v[48:51]
	v_mfma_f32_16x16x32_bf16 v[36:39], v[148:151], v[198:201], v[36:39]
	v_mfma_f32_16x16x32_bf16 v[32:35], v[170:173], v[198:201], v[32:35]
	v_mfma_f32_16x16x32_bf16 v[20:23], v[148:151], v[206:209], v[20:23]
	v_mfma_f32_16x16x32_bf16 v[16:19], v[170:173], v[206:209], v[16:19]
	v_mfma_f32_16x16x32_bf16 v[4:7], v[148:151], v[214:217], v[4:7]
	v_mfma_f32_16x16x32_bf16 v[0:3], v[170:173], v[214:217], v[0:3]
	s_barrier
	s_add_i32 s1, s1, 2
	s_add_u32 s4, s4, 0x100
	s_addc_u32 s5, s5, 0
	s_cmpk_gt_u32 s1, 0x53
	s_mov_b64 s[38:39], s[40:41]
.LBB0_876:
	ds_read_b128 v[128:131], v188
	ds_read_b128 v[132:135], v188 offset:1024
	ds_read_b128 v[136:139], v188 offset:2048
	ds_read_b128 v[140:143], v188 offset:3072
	ds_read_b128 v[144:147], v189
	ds_read_b128 v[148:151], v189 offset:1024
	ds_read_b128 v[166:169], v189 offset:2048
	ds_read_b128 v[170:173], v189 offset:3072
	s_add_u32 s40, s38, 0x100
	s_addc_u32 s41, s39, 0
	s_cmpk_eq_i32 s1, 0x52
	s_cselect_b32 s45, s37, s41
	s_cselect_b32 s44, s36, s40
	s_cselect_b32 s43, s17, s5
	s_cselect_b32 s42, s16, s4
	s_add_i32 m0, s48, 0xc000
	ds_read_b128 v[174:177], v190
	ds_read_b128 v[178:181], v190 offset:1024
	ds_read_b128 v[194:197], v190 offset:2048
	ds_read_b128 v[198:201], v190 offset:3072
	ds_read_b128 v[202:205], v190 offset:4096
	ds_read_b128 v[206:209], v190 offset:5120
	ds_read_b128 v[210:213], v190 offset:6144
	ds_read_b128 v[214:217], v190 offset:7168
	global_load_lds_dwordx4 v160, s[38:39]
	s_add_i32 m0, s48, 0xe000
	s_nop 0
	global_load_lds_dwordx4 v162, s[38:39]
	s_waitcnt vmcnt(8)
	s_waitcnt lgkmcnt(0)
	s_barrier
	v_mfma_f32_16x16x32_bf16 v[124:127], v[128:131], v[174:177], v[124:127]
	v_mfma_f32_16x16x32_bf16 v[120:123], v[136:139], v[174:177], v[120:123]
	v_mfma_f32_16x16x32_bf16 v[108:111], v[128:131], v[194:197], v[108:111]
	v_mfma_f32_16x16x32_bf16 v[104:107], v[136:139], v[194:197], v[104:107]
	v_mfma_f32_16x16x32_bf16 v[92:95], v[128:131], v[202:205], v[92:95]
	v_mfma_f32_16x16x32_bf16 v[88:91], v[136:139], v[202:205], v[88:91]
	v_mfma_f32_16x16x32_bf16 v[76:79], v[128:131], v[210:213], v[76:79]
	v_mfma_f32_16x16x32_bf16 v[72:75], v[136:139], v[210:213], v[72:75]
	v_mfma_f32_16x16x32_bf16 v[124:127], v[132:135], v[178:181], v[124:127]
	v_mfma_f32_16x16x32_bf16 v[120:123], v[140:143], v[178:181], v[120:123]
	v_mfma_f32_16x16x32_bf16 v[108:111], v[132:135], v[198:201], v[108:111]
	v_mfma_f32_16x16x32_bf16 v[104:107], v[140:143], v[198:201], v[104:107]
	v_mfma_f32_16x16x32_bf16 v[92:95], v[132:135], v[206:209], v[92:95]
	v_mfma_f32_16x16x32_bf16 v[88:91], v[140:143], v[206:209], v[88:91]
	v_mfma_f32_16x16x32_bf16 v[76:79], v[132:135], v[214:217], v[76:79]
	v_mfma_f32_16x16x32_bf16 v[72:75], v[140:143], v[214:217], v[72:75]
	v_mfma_f32_16x16x32_bf16 v[116:119], v[144:147], v[174:177], v[116:119]
	v_mfma_f32_16x16x32_bf16 v[112:115], v[166:169], v[174:177], v[112:115]
	v_mfma_f32_16x16x32_bf16 v[100:103], v[144:147], v[194:197], v[100:103]
	v_mfma_f32_16x16x32_bf16 v[96:99], v[166:169], v[194:197], v[96:99]
	v_mfma_f32_16x16x32_bf16 v[84:87], v[144:147], v[202:205], v[84:87]
	v_mfma_f32_16x16x32_bf16 v[80:83], v[166:169], v[202:205], v[80:83]
	v_mfma_f32_16x16x32_bf16 v[68:71], v[144:147], v[210:213], v[68:71]
	v_mfma_f32_16x16x32_bf16 v[64:67], v[166:169], v[210:213], v[64:67]
	v_mfma_f32_16x16x32_bf16 v[116:119], v[148:151], v[178:181], v[116:119]
	v_mfma_f32_16x16x32_bf16 v[112:115], v[170:173], v[178:181], v[112:115]
	v_mfma_f32_16x16x32_bf16 v[100:103], v[148:151], v[198:201], v[100:103]
	v_mfma_f32_16x16x32_bf16 v[96:99], v[170:173], v[198:201], v[96:99]
	v_mfma_f32_16x16x32_bf16 v[84:87], v[148:151], v[206:209], v[84:87]
	v_mfma_f32_16x16x32_bf16 v[80:83], v[170:173], v[206:209], v[80:83]
	v_mfma_f32_16x16x32_bf16 v[68:71], v[148:151], v[214:217], v[68:71]
	v_mfma_f32_16x16x32_bf16 v[64:67], v[170:173], v[214:217], v[64:67]
	s_barrier
	s_add_i32 s3, s70, s33
	s_add_u32 s98, s42, s24
	s_addc_u32 s99, s43, s25
	s_mov_b32 m0, s3
	ds_read_b128 v[174:177], v190 offset:16384
	ds_read_b128 v[178:181], v190 offset:17408
	ds_read_b128 v[194:197], v190 offset:18432
	ds_read_b128 v[198:201], v190 offset:19456
	ds_read_b128 v[202:205], v190 offset:20480
	ds_read_b128 v[206:209], v190 offset:21504
	ds_read_b128 v[210:213], v190 offset:22528
	ds_read_b128 v[214:217], v190 offset:23552
	global_load_lds_dwordx4 v154, s[42:43]
	s_add_i32 m0, s3, 0x2000
	s_add_u32 s38, s42, 0x158000
	s_addc_u32 s39, s43, 0
	s_add_i32 s3, s71, s33
	global_load_lds_dwordx4 v158, s[42:43]
	s_mov_b32 m0, s3
	s_add_u32 s100, s44, s24
	s_addc_u32 s101, s45, s25
	global_load_lds_dwordx4 v154, s[38:39]
	s_add_i32 m0, s3, 0x2000
	s_nop 0
	global_load_lds_dwordx4 v158, s[38:39]
	s_mov_b32 m0, s48
	s_nop 0
	global_load_lds_dwordx4 v152, s[44:45]
	s_mov_b32 m0, s49
	s_nop 0
	global_load_lds_dwordx4 v156, s[44:45]
	s_waitcnt vmcnt(8)
	s_waitcnt lgkmcnt(0)
	s_barrier
	v_mfma_f32_16x16x32_bf16 v[60:63], v[128:131], v[174:177], v[60:63]
	v_mfma_f32_16x16x32_bf16 v[56:59], v[136:139], v[174:177], v[56:59]
	v_mfma_f32_16x16x32_bf16 v[44:47], v[128:131], v[194:197], v[44:47]
	v_mfma_f32_16x16x32_bf16 v[40:43], v[136:139], v[194:197], v[40:43]
	v_mfma_f32_16x16x32_bf16 v[28:31], v[128:131], v[202:205], v[28:31]
	v_mfma_f32_16x16x32_bf16 v[24:27], v[136:139], v[202:205], v[24:27]
	v_mfma_f32_16x16x32_bf16 v[12:15], v[128:131], v[210:213], v[12:15]
	v_mfma_f32_16x16x32_bf16 v[8:11], v[136:139], v[210:213], v[8:11]
	v_mfma_f32_16x16x32_bf16 v[60:63], v[132:135], v[178:181], v[60:63]
	v_mfma_f32_16x16x32_bf16 v[56:59], v[140:143], v[178:181], v[56:59]
	v_mfma_f32_16x16x32_bf16 v[44:47], v[132:135], v[198:201], v[44:47]
	v_mfma_f32_16x16x32_bf16 v[40:43], v[140:143], v[198:201], v[40:43]
	v_mfma_f32_16x16x32_bf16 v[28:31], v[132:135], v[206:209], v[28:31]
	v_mfma_f32_16x16x32_bf16 v[24:27], v[140:143], v[206:209], v[24:27]
	v_mfma_f32_16x16x32_bf16 v[12:15], v[132:135], v[214:217], v[12:15]
	v_mfma_f32_16x16x32_bf16 v[8:11], v[140:143], v[214:217], v[8:11]
	v_mfma_f32_16x16x32_bf16 v[52:55], v[144:147], v[174:177], v[52:55]
	v_mfma_f32_16x16x32_bf16 v[48:51], v[166:169], v[174:177], v[48:51]
	v_mfma_f32_16x16x32_bf16 v[36:39], v[144:147], v[194:197], v[36:39]
	v_mfma_f32_16x16x32_bf16 v[32:35], v[166:169], v[194:197], v[32:35]
	v_mfma_f32_16x16x32_bf16 v[20:23], v[144:147], v[202:205], v[20:23]
	v_mfma_f32_16x16x32_bf16 v[16:19], v[166:169], v[202:205], v[16:19]
	v_mfma_f32_16x16x32_bf16 v[4:7], v[144:147], v[210:213], v[4:7]
	v_mfma_f32_16x16x32_bf16 v[0:3], v[166:169], v[210:213], v[0:3]
	v_mfma_f32_16x16x32_bf16 v[52:55], v[148:151], v[178:181], v[52:55]
	v_mfma_f32_16x16x32_bf16 v[48:51], v[170:173], v[178:181], v[48:51]
	v_mfma_f32_16x16x32_bf16 v[36:39], v[148:151], v[198:201], v[36:39]
	v_mfma_f32_16x16x32_bf16 v[32:35], v[170:173], v[198:201], v[32:35]
	v_mfma_f32_16x16x32_bf16 v[20:23], v[148:151], v[206:209], v[20:23]
	v_mfma_f32_16x16x32_bf16 v[16:19], v[170:173], v[206:209], v[16:19]
	v_mfma_f32_16x16x32_bf16 v[4:7], v[148:151], v[214:217], v[4:7]
	v_mfma_f32_16x16x32_bf16 v[0:3], v[170:173], v[214:217], v[0:3]
	s_barrier
	s_add_i32 s3, 0, 0x18000
	s_add_i32 s73, 0, 0x1c000
	v_add_u32_e32 v140, s3, v187
	v_add_u32_e32 v170, s73, v187
	ds_read_b128 v[128:131], v140
	ds_read_b128 v[132:135], v140 offset:1024
	ds_read_b128 v[136:139], v140 offset:2048
	ds_read_b128 v[140:143], v140 offset:3072
	ds_read_b128 v[144:147], v170
	ds_read_b128 v[148:151], v170 offset:1024
	ds_read_b128 v[166:169], v170 offset:2048
	ds_read_b128 v[170:173], v170 offset:3072
	s_add_u32 s38, s44, 0x158000
	s_addc_u32 s39, s45, 0
	s_mov_b32 m0, s51
	ds_read_b128 v[174:177], v190 offset:32768
	ds_read_b128 v[178:181], v190 offset:33792
	ds_read_b128 v[194:197], v190 offset:34816
	ds_read_b128 v[198:201], v190 offset:35840
	ds_read_b128 v[202:205], v190 offset:36864
	ds_read_b128 v[206:209], v190 offset:37888
	ds_read_b128 v[210:213], v190 offset:38912
	ds_read_b128 v[214:217], v190 offset:39936
	global_load_lds_dwordx4 v152, s[38:39]
	s_mov_b32 m0, s52
	s_nop 0
	global_load_lds_dwordx4 v156, s[38:39]
	s_waitcnt vmcnt(8)
	s_waitcnt lgkmcnt(0)
	s_barrier
	v_mfma_f32_16x16x32_bf16 v[124:127], v[128:131], v[174:177], v[124:127]
	v_mfma_f32_16x16x32_bf16 v[120:123], v[136:139], v[174:177], v[120:123]
	v_mfma_f32_16x16x32_bf16 v[108:111], v[128:131], v[194:197], v[108:111]
	v_mfma_f32_16x16x32_bf16 v[104:107], v[136:139], v[194:197], v[104:107]
	v_mfma_f32_16x16x32_bf16 v[92:95], v[128:131], v[202:205], v[92:95]
	v_mfma_f32_16x16x32_bf16 v[88:91], v[136:139], v[202:205], v[88:91]
	v_mfma_f32_16x16x32_bf16 v[76:79], v[128:131], v[210:213], v[76:79]
	v_mfma_f32_16x16x32_bf16 v[72:75], v[136:139], v[210:213], v[72:75]
	v_mfma_f32_16x16x32_bf16 v[124:127], v[132:135], v[178:181], v[124:127]
	v_mfma_f32_16x16x32_bf16 v[120:123], v[140:143], v[178:181], v[120:123]
	v_mfma_f32_16x16x32_bf16 v[108:111], v[132:135], v[198:201], v[108:111]
	v_mfma_f32_16x16x32_bf16 v[104:107], v[140:143], v[198:201], v[104:107]
	v_mfma_f32_16x16x32_bf16 v[92:95], v[132:135], v[206:209], v[92:95]
	v_mfma_f32_16x16x32_bf16 v[88:91], v[140:143], v[206:209], v[88:91]
	v_mfma_f32_16x16x32_bf16 v[76:79], v[132:135], v[214:217], v[76:79]
	v_mfma_f32_16x16x32_bf16 v[72:75], v[140:143], v[214:217], v[72:75]
	v_mfma_f32_16x16x32_bf16 v[116:119], v[144:147], v[174:177], v[116:119]
	v_mfma_f32_16x16x32_bf16 v[112:115], v[166:169], v[174:177], v[112:115]
	v_mfma_f32_16x16x32_bf16 v[100:103], v[144:147], v[194:197], v[100:103]
	v_mfma_f32_16x16x32_bf16 v[96:99], v[166:169], v[194:197], v[96:99]
	v_mfma_f32_16x16x32_bf16 v[84:87], v[144:147], v[202:205], v[84:87]
	v_mfma_f32_16x16x32_bf16 v[80:83], v[166:169], v[202:205], v[80:83]
	v_mfma_f32_16x16x32_bf16 v[68:71], v[144:147], v[210:213], v[68:71]
	v_mfma_f32_16x16x32_bf16 v[64:67], v[166:169], v[210:213], v[64:67]
	v_mfma_f32_16x16x32_bf16 v[116:119], v[148:151], v[178:181], v[116:119]
	v_mfma_f32_16x16x32_bf16 v[112:115], v[170:173], v[178:181], v[112:115]
	v_mfma_f32_16x16x32_bf16 v[100:103], v[148:151], v[198:201], v[100:103]
	v_mfma_f32_16x16x32_bf16 v[96:99], v[170:173], v[198:201], v[96:99]
	v_mfma_f32_16x16x32_bf16 v[84:87], v[148:151], v[206:209], v[84:87]
	v_mfma_f32_16x16x32_bf16 v[80:83], v[170:173], v[206:209], v[80:83]
	v_mfma_f32_16x16x32_bf16 v[68:71], v[148:151], v[214:217], v[68:71]
	v_mfma_f32_16x16x32_bf16 v[64:67], v[170:173], v[214:217], v[64:67]
	s_barrier
	s_add_i32 s3, s3, s33
	s_mov_b32 m0, s3
	ds_read_b128 v[174:177], v190 offset:49152
	ds_read_b128 v[178:181], v190 offset:50176
	ds_read_b128 v[194:197], v190 offset:51200
	ds_read_b128 v[198:201], v190 offset:52224
	ds_read_b128 v[202:205], v190 offset:53248
	ds_read_b128 v[206:209], v190 offset:54272
	ds_read_b128 v[210:213], v190 offset:55296
	ds_read_b128 v[214:217], v190 offset:56320
	global_load_lds_dwordx4 v154, s[98:99]
	s_add_i32 m0, s3, 0x2000
	s_add_u32 s38, s42, 0x158080
	s_addc_u32 s39, s43, 0
	s_add_i32 s3, s73, s33
	global_load_lds_dwordx4 v158, s[98:99]
	s_mov_b32 m0, s3
	s_nop 0
	global_load_lds_dwordx4 v154, s[38:39]
	s_add_i32 m0, s3, 0x2000
	s_nop 0
	global_load_lds_dwordx4 v158, s[38:39]
	s_mov_b32 m0, s56
	s_nop 0
	global_load_lds_dwordx4 v152, s[100:101]
	s_mov_b32 m0, s57
	s_nop 0
	global_load_lds_dwordx4 v156, s[100:101]
	s_waitcnt vmcnt(8)
	s_waitcnt lgkmcnt(0)
	s_barrier
	v_mfma_f32_16x16x32_bf16 v[60:63], v[128:131], v[174:177], v[60:63]
	v_mfma_f32_16x16x32_bf16 v[56:59], v[136:139], v[174:177], v[56:59]
	v_mfma_f32_16x16x32_bf16 v[44:47], v[128:131], v[194:197], v[44:47]
	v_mfma_f32_16x16x32_bf16 v[40:43], v[136:139], v[194:197], v[40:43]
	v_mfma_f32_16x16x32_bf16 v[28:31], v[128:131], v[202:205], v[28:31]
	v_mfma_f32_16x16x32_bf16 v[24:27], v[136:139], v[202:205], v[24:27]
	v_mfma_f32_16x16x32_bf16 v[12:15], v[128:131], v[210:213], v[12:15]
	v_mfma_f32_16x16x32_bf16 v[8:11], v[136:139], v[210:213], v[8:11]
	v_mfma_f32_16x16x32_bf16 v[60:63], v[132:135], v[178:181], v[60:63]
	v_mfma_f32_16x16x32_bf16 v[56:59], v[140:143], v[178:181], v[56:59]
	v_mfma_f32_16x16x32_bf16 v[44:47], v[132:135], v[198:201], v[44:47]
	v_mfma_f32_16x16x32_bf16 v[40:43], v[140:143], v[198:201], v[40:43]
	v_mfma_f32_16x16x32_bf16 v[28:31], v[132:135], v[206:209], v[28:31]
	v_mfma_f32_16x16x32_bf16 v[24:27], v[140:143], v[206:209], v[24:27]
	v_mfma_f32_16x16x32_bf16 v[12:15], v[132:135], v[214:217], v[12:15]
	v_mfma_f32_16x16x32_bf16 v[8:11], v[140:143], v[214:217], v[8:11]
	v_mfma_f32_16x16x32_bf16 v[52:55], v[144:147], v[174:177], v[52:55]
	v_mfma_f32_16x16x32_bf16 v[48:51], v[166:169], v[174:177], v[48:51]
	v_mfma_f32_16x16x32_bf16 v[36:39], v[144:147], v[194:197], v[36:39]
	v_mfma_f32_16x16x32_bf16 v[32:35], v[166:169], v[194:197], v[32:35]
	v_mfma_f32_16x16x32_bf16 v[20:23], v[144:147], v[202:205], v[20:23]
	v_mfma_f32_16x16x32_bf16 v[16:19], v[166:169], v[202:205], v[16:19]
	v_mfma_f32_16x16x32_bf16 v[4:7], v[144:147], v[210:213], v[4:7]
	v_mfma_f32_16x16x32_bf16 v[0:3], v[166:169], v[210:213], v[0:3]
	v_mfma_f32_16x16x32_bf16 v[52:55], v[148:151], v[178:181], v[52:55]
	v_mfma_f32_16x16x32_bf16 v[48:51], v[170:173], v[178:181], v[48:51]
	v_mfma_f32_16x16x32_bf16 v[36:39], v[148:151], v[198:201], v[36:39]
	v_mfma_f32_16x16x32_bf16 v[32:35], v[170:173], v[198:201], v[32:35]
	v_mfma_f32_16x16x32_bf16 v[20:23], v[148:151], v[206:209], v[20:23]
	v_mfma_f32_16x16x32_bf16 v[16:19], v[170:173], v[206:209], v[16:19]
	v_mfma_f32_16x16x32_bf16 v[4:7], v[148:151], v[214:217], v[4:7]
	v_mfma_f32_16x16x32_bf16 v[0:3], v[170:173], v[214:217], v[0:3]
	s_barrier
	s_add_i32 s1, s1, 2
	s_add_u32 s4, s4, 0x100
	s_addc_u32 s5, s5, 0
	s_cmpk_gt_u32 s1, 0x53
	s_mov_b64 s[38:39], s[40:41]
	s_cbranch_scc0 .LBB0_876
	s_and_b64 vcc, exec, s[26:27]
	s_cbranch_vccz .LBB0_879
	s_barrier
